# GEMM MFMA order: back-to-back k0,k1 on one accumulator, weight-fragment pair held over a serpentine sweep of the 4 activation fragments (less register traffic); + tile-order groups of 4
# speedup vs baseline: 1.0232x; 1.0144x over previous
.LBB0_119:
	ds_read_b128 v[150:153], v147
	ds_read_b128 v[154:157], v147 offset:1024
	ds_read_b128 v[158:161], v147 offset:2048
	ds_read_b128 v[162:165], v147 offset:3072
	ds_read_b128 v[166:169], v148
	ds_read_b128 v[170:173], v148 offset:1024
	ds_read_b128 v[174:177], v148 offset:2048
	ds_read_b128 v[178:181], v148 offset:3072
	s_add_u32 s20, s54, 0xfffc0080
	s_addc_u32 s21, s55, -1
	s_cmp_eq_u32 s89, 12
	s_cselect_b32 s59, s19, s21
	s_cselect_b32 s58, s85, s20
	s_cselect_b32 s57, s17, s88
	s_cselect_b32 s56, s86, s87
	v_lshl_add_u64 v[214:215], s[54:55], 0, v[136:137]
	s_add_i32 m0, s51, 0xc000
	ds_read_b128 v[182:185], v149
	ds_read_b128 v[186:189], v149 offset:1024
	ds_read_b128 v[190:193], v149 offset:2048
	ds_read_b128 v[194:197], v149 offset:3072
	ds_read_b128 v[198:201], v149 offset:4096
	ds_read_b128 v[202:205], v149 offset:5120
	ds_read_b128 v[206:209], v149 offset:6144
	ds_read_b128 v[210:213], v149 offset:7168
	global_load_lds_dwordx4 v[214:215], off
	v_lshl_add_u64 v[214:215], s[54:55], 0, v[138:139]
	s_add_i32 m0, s51, 0xe000
	s_nop 0
	global_load_lds_dwordx4 v[214:215], off
	s_waitcnt vmcnt(8)
	s_waitcnt lgkmcnt(0)
	s_barrier
	s_setprio 1
	s_waitcnt lgkmcnt(0)
	v_mfma_f32_16x16x32_bf16 v[124:127], v[150:153], v[182:185], v[124:127]
	v_mfma_f32_16x16x32_bf16 v[124:127], v[154:157], v[186:189], v[124:127]
	v_mfma_f32_16x16x32_bf16 v[108:111], v[150:153], v[190:193], v[108:111]
	v_mfma_f32_16x16x32_bf16 v[108:111], v[154:157], v[194:197], v[108:111]
	v_mfma_f32_16x16x32_bf16 v[92:95], v[150:153], v[198:201], v[92:95]
	v_mfma_f32_16x16x32_bf16 v[92:95], v[154:157], v[202:205], v[92:95]
	v_mfma_f32_16x16x32_bf16 v[76:79], v[150:153], v[206:209], v[76:79]
	v_mfma_f32_16x16x32_bf16 v[76:79], v[154:157], v[210:213], v[76:79]
	v_mfma_f32_16x16x32_bf16 v[68:71], v[158:161], v[206:209], v[68:71]
	v_mfma_f32_16x16x32_bf16 v[68:71], v[162:165], v[210:213], v[68:71]
	v_mfma_f32_16x16x32_bf16 v[84:87], v[158:161], v[198:201], v[84:87]
	v_mfma_f32_16x16x32_bf16 v[84:87], v[162:165], v[202:205], v[84:87]
	v_mfma_f32_16x16x32_bf16 v[100:103], v[158:161], v[190:193], v[100:103]
	v_mfma_f32_16x16x32_bf16 v[100:103], v[162:165], v[194:197], v[100:103]
	v_mfma_f32_16x16x32_bf16 v[116:119], v[158:161], v[182:185], v[116:119]
	v_mfma_f32_16x16x32_bf16 v[116:119], v[162:165], v[186:189], v[116:119]
	s_setprio 0
	s_setprio 1
	v_mfma_f32_16x16x32_bf16 v[120:123], v[166:169], v[182:185], v[120:123]
	v_mfma_f32_16x16x32_bf16 v[120:123], v[170:173], v[186:189], v[120:123]
	v_mfma_f32_16x16x32_bf16 v[104:107], v[166:169], v[190:193], v[104:107]
	v_mfma_f32_16x16x32_bf16 v[104:107], v[170:173], v[194:197], v[104:107]
	v_mfma_f32_16x16x32_bf16 v[88:91], v[166:169], v[198:201], v[88:91]
	v_mfma_f32_16x16x32_bf16 v[88:91], v[170:173], v[202:205], v[88:91]
	v_mfma_f32_16x16x32_bf16 v[72:75], v[166:169], v[206:209], v[72:75]
	v_mfma_f32_16x16x32_bf16 v[72:75], v[170:173], v[210:213], v[72:75]
	v_mfma_f32_16x16x32_bf16 v[64:67], v[174:177], v[206:209], v[64:67]
	v_mfma_f32_16x16x32_bf16 v[64:67], v[178:181], v[210:213], v[64:67]
	v_mfma_f32_16x16x32_bf16 v[80:83], v[174:177], v[198:201], v[80:83]
	v_mfma_f32_16x16x32_bf16 v[80:83], v[178:181], v[202:205], v[80:83]
	v_mfma_f32_16x16x32_bf16 v[96:99], v[174:177], v[190:193], v[96:99]
	v_mfma_f32_16x16x32_bf16 v[96:99], v[178:181], v[194:197], v[96:99]
	v_mfma_f32_16x16x32_bf16 v[112:115], v[174:177], v[182:185], v[112:115]
	v_mfma_f32_16x16x32_bf16 v[112:115], v[178:181], v[186:189], v[112:115]
	s_setprio 0
	s_barrier
	s_add_i32 s20, s81, s60
	v_lshl_add_u64 v[214:215], s[56:57], 0, v[132:133]
	s_mov_b32 m0, s20
	ds_read_b128 v[182:185], v149 offset:16384
	ds_read_b128 v[186:189], v149 offset:17408
	ds_read_b128 v[190:193], v149 offset:18432
	ds_read_b128 v[194:197], v149 offset:19456
	ds_read_b128 v[198:201], v149 offset:20480
	ds_read_b128 v[202:205], v149 offset:21504
	ds_read_b128 v[206:209], v149 offset:22528
	ds_read_b128 v[210:213], v149 offset:23552
	global_load_lds_dwordx4 v[214:215], off
	s_add_i32 m0, s20, 0x2000
	s_add_u32 s20, s56, 0x40000
	v_lshl_add_u64 v[216:217], s[56:57], 0, v[128:129]
	s_addc_u32 s21, s57, 0
	s_add_i32 s33, s82, s60
	global_load_lds_dwordx4 v[216:217], off
	v_lshl_add_u64 v[218:219], s[20:21], 0, v[132:133]
	s_mov_b32 m0, s33
	v_lshl_add_u64 v[220:221], s[58:59], 0, v[130:131]
	global_load_lds_dwordx4 v[218:219], off
	v_lshl_add_u64 v[218:219], s[20:21], 0, v[128:129]
	s_add_i32 m0, s33, 0x2000
	s_nop 0
	global_load_lds_dwordx4 v[218:219], off
	v_lshl_add_u64 v[218:219], s[58:59], 0, v[134:135]
	s_mov_b32 m0, s51
	s_nop 0
	global_load_lds_dwordx4 v[218:219], off
	s_mov_b32 m0, s63
	s_nop 0
	global_load_lds_dwordx4 v[220:221], off
	s_waitcnt vmcnt(8)
	s_waitcnt lgkmcnt(0)
	s_barrier
	s_setprio 1
	s_waitcnt lgkmcnt(0)
	v_mfma_f32_16x16x32_bf16 v[60:63], v[150:153], v[182:185], v[60:63]
	v_mfma_f32_16x16x32_bf16 v[60:63], v[154:157], v[186:189], v[60:63]
	v_mfma_f32_16x16x32_bf16 v[44:47], v[150:153], v[190:193], v[44:47]
	v_mfma_f32_16x16x32_bf16 v[44:47], v[154:157], v[194:197], v[44:47]
	v_mfma_f32_16x16x32_bf16 v[28:31], v[150:153], v[198:201], v[28:31]
	v_mfma_f32_16x16x32_bf16 v[28:31], v[154:157], v[202:205], v[28:31]
	v_mfma_f32_16x16x32_bf16 v[12:15], v[150:153], v[206:209], v[12:15]
	v_mfma_f32_16x16x32_bf16 v[12:15], v[154:157], v[210:213], v[12:15]
	v_mfma_f32_16x16x32_bf16 v[4:7], v[158:161], v[206:209], v[4:7]
	v_mfma_f32_16x16x32_bf16 v[4:7], v[162:165], v[210:213], v[4:7]
	v_mfma_f32_16x16x32_bf16 v[20:23], v[158:161], v[198:201], v[20:23]
	v_mfma_f32_16x16x32_bf16 v[20:23], v[162:165], v[202:205], v[20:23]
	v_mfma_f32_16x16x32_bf16 v[36:39], v[158:161], v[190:193], v[36:39]
	v_mfma_f32_16x16x32_bf16 v[36:39], v[162:165], v[194:197], v[36:39]
	v_mfma_f32_16x16x32_bf16 v[52:55], v[158:161], v[182:185], v[52:55]
	v_mfma_f32_16x16x32_bf16 v[52:55], v[162:165], v[186:189], v[52:55]
	s_setprio 0
	s_setprio 1
	v_mfma_f32_16x16x32_bf16 v[56:59], v[166:169], v[182:185], v[56:59]
	v_mfma_f32_16x16x32_bf16 v[56:59], v[170:173], v[186:189], v[56:59]
	v_mfma_f32_16x16x32_bf16 v[40:43], v[166:169], v[190:193], v[40:43]
	v_mfma_f32_16x16x32_bf16 v[40:43], v[170:173], v[194:197], v[40:43]
	v_mfma_f32_16x16x32_bf16 v[24:27], v[166:169], v[198:201], v[24:27]
	v_mfma_f32_16x16x32_bf16 v[24:27], v[170:173], v[202:205], v[24:27]
	v_mfma_f32_16x16x32_bf16 v[8:11], v[166:169], v[206:209], v[8:11]
	v_mfma_f32_16x16x32_bf16 v[8:11], v[170:173], v[210:213], v[8:11]
	v_mfma_f32_16x16x32_bf16 v[0:3], v[174:177], v[206:209], v[0:3]
	v_mfma_f32_16x16x32_bf16 v[0:3], v[178:181], v[210:213], v[0:3]
	v_mfma_f32_16x16x32_bf16 v[16:19], v[174:177], v[198:201], v[16:19]
	v_mfma_f32_16x16x32_bf16 v[16:19], v[178:181], v[202:205], v[16:19]
	v_mfma_f32_16x16x32_bf16 v[32:35], v[174:177], v[190:193], v[32:35]
	v_mfma_f32_16x16x32_bf16 v[32:35], v[178:181], v[194:197], v[32:35]
	v_mfma_f32_16x16x32_bf16 v[48:51], v[174:177], v[182:185], v[48:51]
	v_mfma_f32_16x16x32_bf16 v[48:51], v[178:181], v[186:189], v[48:51]
	s_setprio 0
	s_barrier
	s_add_i32 s33, 0, 0x18000
	s_add_i32 s75, 0, 0x1c000
	v_add_u32_e32 v162, s33, v145
	v_add_u32_e32 v178, s75, v145
	ds_read_b128 v[150:153], v162
	ds_read_b128 v[154:157], v162 offset:1024
	ds_read_b128 v[158:161], v162 offset:2048
	ds_read_b128 v[162:165], v162 offset:3072
	ds_read_b128 v[166:169], v178
	ds_read_b128 v[170:173], v178 offset:1024
	ds_read_b128 v[174:177], v178 offset:2048
	ds_read_b128 v[178:181], v178 offset:3072
	s_add_u32 s20, s58, 0x40000
	s_addc_u32 s21, s59, 0
	s_mov_b32 m0, s64
	v_lshl_add_u64 v[222:223], s[20:21], 0, v[134:135]
	ds_read_b128 v[182:185], v149 offset:32768
	ds_read_b128 v[186:189], v149 offset:33792
	ds_read_b128 v[190:193], v149 offset:34816
	ds_read_b128 v[194:197], v149 offset:35840
	ds_read_b128 v[198:201], v149 offset:36864
	ds_read_b128 v[202:205], v149 offset:37888
	ds_read_b128 v[206:209], v149 offset:38912
	ds_read_b128 v[210:213], v149 offset:39936
	global_load_lds_dwordx4 v[222:223], off
	v_lshl_add_u64 v[222:223], s[20:21], 0, v[130:131]
	s_mov_b32 m0, s65
	s_nop 0
	global_load_lds_dwordx4 v[222:223], off
	s_waitcnt vmcnt(8)
	s_waitcnt lgkmcnt(0)
	s_barrier
	s_setprio 1
	s_waitcnt lgkmcnt(0)
	v_mfma_f32_16x16x32_bf16 v[124:127], v[150:153], v[182:185], v[124:127]
	v_mfma_f32_16x16x32_bf16 v[124:127], v[154:157], v[186:189], v[124:127]
	v_mfma_f32_16x16x32_bf16 v[108:111], v[150:153], v[190:193], v[108:111]
	v_mfma_f32_16x16x32_bf16 v[108:111], v[154:157], v[194:197], v[108:111]
	v_mfma_f32_16x16x32_bf16 v[92:95], v[150:153], v[198:201], v[92:95]
	v_mfma_f32_16x16x32_bf16 v[92:95], v[154:157], v[202:205], v[92:95]
	v_mfma_f32_16x16x32_bf16 v[76:79], v[150:153], v[206:209], v[76:79]
	v_mfma_f32_16x16x32_bf16 v[76:79], v[154:157], v[210:213], v[76:79]
	v_mfma_f32_16x16x32_bf16 v[68:71], v[158:161], v[206:209], v[68:71]
	v_mfma_f32_16x16x32_bf16 v[68:71], v[162:165], v[210:213], v[68:71]
	v_mfma_f32_16x16x32_bf16 v[84:87], v[158:161], v[198:201], v[84:87]
	v_mfma_f32_16x16x32_bf16 v[84:87], v[162:165], v[202:205], v[84:87]
	v_mfma_f32_16x16x32_bf16 v[100:103], v[158:161], v[190:193], v[100:103]
	v_mfma_f32_16x16x32_bf16 v[100:103], v[162:165], v[194:197], v[100:103]
	v_mfma_f32_16x16x32_bf16 v[116:119], v[158:161], v[182:185], v[116:119]
	v_mfma_f32_16x16x32_bf16 v[116:119], v[162:165], v[186:189], v[116:119]
	s_setprio 0
	s_setprio 1
	v_mfma_f32_16x16x32_bf16 v[120:123], v[166:169], v[182:185], v[120:123]
	v_mfma_f32_16x16x32_bf16 v[120:123], v[170:173], v[186:189], v[120:123]
	v_mfma_f32_16x16x32_bf16 v[104:107], v[166:169], v[190:193], v[104:107]
	v_mfma_f32_16x16x32_bf16 v[104:107], v[170:173], v[194:197], v[104:107]
	v_mfma_f32_16x16x32_bf16 v[88:91], v[166:169], v[198:201], v[88:91]
	v_mfma_f32_16x16x32_bf16 v[88:91], v[170:173], v[202:205], v[88:91]
	v_mfma_f32_16x16x32_bf16 v[72:75], v[166:169], v[206:209], v[72:75]
	v_mfma_f32_16x16x32_bf16 v[72:75], v[170:173], v[210:213], v[72:75]
	v_mfma_f32_16x16x32_bf16 v[64:67], v[174:177], v[206:209], v[64:67]
	v_mfma_f32_16x16x32_bf16 v[64:67], v[178:181], v[210:213], v[64:67]
	v_mfma_f32_16x16x32_bf16 v[80:83], v[174:177], v[198:201], v[80:83]
	v_mfma_f32_16x16x32_bf16 v[80:83], v[178:181], v[202:205], v[80:83]
	v_mfma_f32_16x16x32_bf16 v[96:99], v[174:177], v[190:193], v[96:99]
	v_mfma_f32_16x16x32_bf16 v[96:99], v[178:181], v[194:197], v[96:99]
	v_mfma_f32_16x16x32_bf16 v[112:115], v[174:177], v[182:185], v[112:115]
	v_mfma_f32_16x16x32_bf16 v[112:115], v[178:181], v[186:189], v[112:115]
	s_setprio 0
	s_barrier
	s_add_i32 s20, s33, s60
	v_lshl_add_u64 v[214:215], v[214:215], 0, s[6:7]
	s_mov_b32 m0, s20
	ds_read_b128 v[182:185], v149 offset:49152
	ds_read_b128 v[186:189], v149 offset:50176
	ds_read_b128 v[190:193], v149 offset:51200
	ds_read_b128 v[194:197], v149 offset:52224
	ds_read_b128 v[198:201], v149 offset:53248
	ds_read_b128 v[202:205], v149 offset:54272
	ds_read_b128 v[206:209], v149 offset:55296
	ds_read_b128 v[210:213], v149 offset:56320
	global_load_lds_dwordx4 v[214:215], off
	s_add_i32 m0, s20, 0x2000
	s_add_u32 s20, s56, 0x40080
	v_lshl_add_u64 v[214:215], v[216:217], 0, s[6:7]
	s_addc_u32 s21, s57, 0
	s_add_i32 s33, s75, s60
	global_load_lds_dwordx4 v[214:215], off
	v_lshl_add_u64 v[214:215], s[20:21], 0, v[132:133]
	s_mov_b32 m0, s33
	s_nop 0
	global_load_lds_dwordx4 v[214:215], off
	v_lshl_add_u64 v[214:215], s[20:21], 0, v[128:129]
	s_add_i32 m0, s33, 0x2000
	s_nop 0
	global_load_lds_dwordx4 v[214:215], off
	v_lshl_add_u64 v[214:215], v[218:219], 0, s[6:7]
	s_mov_b32 m0, s77
	s_nop 0
	global_load_lds_dwordx4 v[214:215], off
	v_lshl_add_u64 v[214:215], v[220:221], 0, s[6:7]
	s_mov_b32 m0, s78
	s_nop 0
	global_load_lds_dwordx4 v[214:215], off
	s_waitcnt vmcnt(8)
	s_waitcnt lgkmcnt(0)
	s_barrier
	s_setprio 1
	s_waitcnt lgkmcnt(0)
	v_mfma_f32_16x16x32_bf16 v[60:63], v[150:153], v[182:185], v[60:63]
	v_mfma_f32_16x16x32_bf16 v[60:63], v[154:157], v[186:189], v[60:63]
	v_mfma_f32_16x16x32_bf16 v[44:47], v[150:153], v[190:193], v[44:47]
	v_mfma_f32_16x16x32_bf16 v[44:47], v[154:157], v[194:197], v[44:47]
	v_mfma_f32_16x16x32_bf16 v[28:31], v[150:153], v[198:201], v[28:31]
	v_mfma_f32_16x16x32_bf16 v[28:31], v[154:157], v[202:205], v[28:31]
	v_mfma_f32_16x16x32_bf16 v[12:15], v[150:153], v[206:209], v[12:15]
	v_mfma_f32_16x16x32_bf16 v[12:15], v[154:157], v[210:213], v[12:15]
	v_mfma_f32_16x16x32_bf16 v[4:7], v[158:161], v[206:209], v[4:7]
	v_mfma_f32_16x16x32_bf16 v[4:7], v[162:165], v[210:213], v[4:7]
	v_mfma_f32_16x16x32_bf16 v[20:23], v[158:161], v[198:201], v[20:23]
	v_mfma_f32_16x16x32_bf16 v[20:23], v[162:165], v[202:205], v[20:23]
	v_mfma_f32_16x16x32_bf16 v[36:39], v[158:161], v[190:193], v[36:39]
	v_mfma_f32_16x16x32_bf16 v[36:39], v[162:165], v[194:197], v[36:39]
	v_mfma_f32_16x16x32_bf16 v[52:55], v[158:161], v[182:185], v[52:55]
	v_mfma_f32_16x16x32_bf16 v[52:55], v[162:165], v[186:189], v[52:55]
	s_setprio 0
	s_setprio 1
	v_mfma_f32_16x16x32_bf16 v[56:59], v[166:169], v[182:185], v[56:59]
	v_mfma_f32_16x16x32_bf16 v[56:59], v[170:173], v[186:189], v[56:59]
	v_mfma_f32_16x16x32_bf16 v[40:43], v[166:169], v[190:193], v[40:43]
	v_mfma_f32_16x16x32_bf16 v[40:43], v[170:173], v[194:197], v[40:43]
	v_mfma_f32_16x16x32_bf16 v[24:27], v[166:169], v[198:201], v[24:27]
	v_mfma_f32_16x16x32_bf16 v[24:27], v[170:173], v[202:205], v[24:27]
	v_mfma_f32_16x16x32_bf16 v[8:11], v[166:169], v[206:209], v[8:11]
	v_mfma_f32_16x16x32_bf16 v[8:11], v[170:173], v[210:213], v[8:11]
	v_mfma_f32_16x16x32_bf16 v[0:3], v[174:177], v[206:209], v[0:3]
	v_mfma_f32_16x16x32_bf16 v[0:3], v[178:181], v[210:213], v[0:3]
	v_mfma_f32_16x16x32_bf16 v[16:19], v[174:177], v[198:201], v[16:19]
	v_mfma_f32_16x16x32_bf16 v[16:19], v[178:181], v[202:205], v[16:19]
	v_mfma_f32_16x16x32_bf16 v[32:35], v[174:177], v[190:193], v[32:35]
	v_mfma_f32_16x16x32_bf16 v[32:35], v[178:181], v[194:197], v[32:35]
	v_mfma_f32_16x16x32_bf16 v[48:51], v[174:177], v[182:185], v[48:51]
	v_mfma_f32_16x16x32_bf16 v[48:51], v[178:181], v[186:189], v[48:51]
	s_setprio 0
	s_barrier
	s_add_i32 s89, s89, 2
	s_add_u32 s54, s54, 0x100
	s_addc_u32 s55, s55, 0
	s_add_u32 s87, s87, 0x100
	s_addc_u32 s88, s88, 0
	s_cmp_gt_u32 s89, 13
	s_cbranch_scc0 .LBB0_119
	s_and_b64 vcc, exec, s[8:9]
	s_cbranch_vccz .LBB0_122
	s_barrier

.LBB0_201:
	ds_read_b128 v[128:131], v207
	ds_read_b128 v[132:135], v207 offset:1024
	ds_read_b128 v[136:139], v207 offset:2048
	ds_read_b128 v[140:143], v207 offset:3072
	ds_read_b128 v[144:147], v208
	ds_read_b128 v[148:151], v208 offset:1024
	ds_read_b128 v[152:155], v208 offset:2048
	ds_read_b128 v[156:159], v208 offset:3072
	s_add_u32 s56, s54, 0x100
	s_addc_u32 s57, s55, 0
	s_cmp_eq_u32 s91, 40
	s_cselect_b32 s61, s1, s57
	s_cselect_b32 s60, s0, s56
	s_cselect_b32 s59, s51, s90
	s_cselect_b32 s58, s50, s89
	v_lshl_add_u64 v[216:217], s[54:55], 0, v[184:185]
	s_add_i32 m0, s63, 0xc000
	ds_read_b128 v[160:163], v209
	ds_read_b128 v[164:167], v209 offset:1024
	ds_read_b128 v[168:171], v209 offset:2048
	ds_read_b128 v[172:175], v209 offset:3072
	ds_read_b128 v[192:195], v209 offset:4096
	ds_read_b128 v[196:199], v209 offset:5120
	ds_read_b128 v[200:203], v209 offset:6144
	ds_read_b128 v[212:215], v209 offset:7168
	global_load_lds_dwordx4 v[216:217], off
	v_lshl_add_u64 v[216:217], s[54:55], 0, v[186:187]
	s_add_i32 m0, s63, 0xe000
	s_nop 0
	global_load_lds_dwordx4 v[216:217], off
	s_waitcnt vmcnt(8)
	s_waitcnt lgkmcnt(0)
	s_barrier
	s_setprio 1
	s_waitcnt lgkmcnt(0)
	v_mfma_f32_16x16x32_bf16 v[124:127], v[128:131], v[160:163], v[124:127]
	v_mfma_f32_16x16x32_bf16 v[124:127], v[132:135], v[164:167], v[124:127]
	v_mfma_f32_16x16x32_bf16 v[108:111], v[128:131], v[168:171], v[108:111]
	v_mfma_f32_16x16x32_bf16 v[108:111], v[132:135], v[172:175], v[108:111]
	v_mfma_f32_16x16x32_bf16 v[92:95], v[128:131], v[192:195], v[92:95]
	v_mfma_f32_16x16x32_bf16 v[92:95], v[132:135], v[196:199], v[92:95]
	v_mfma_f32_16x16x32_bf16 v[76:79], v[128:131], v[200:203], v[76:79]
	v_mfma_f32_16x16x32_bf16 v[76:79], v[132:135], v[212:215], v[76:79]
	v_mfma_f32_16x16x32_bf16 v[72:75], v[136:139], v[200:203], v[72:75]
	v_mfma_f32_16x16x32_bf16 v[72:75], v[140:143], v[212:215], v[72:75]
	v_mfma_f32_16x16x32_bf16 v[88:91], v[136:139], v[192:195], v[88:91]
	v_mfma_f32_16x16x32_bf16 v[88:91], v[140:143], v[196:199], v[88:91]
	v_mfma_f32_16x16x32_bf16 v[104:107], v[136:139], v[168:171], v[104:107]
	v_mfma_f32_16x16x32_bf16 v[104:107], v[140:143], v[172:175], v[104:107]
	v_mfma_f32_16x16x32_bf16 v[120:123], v[136:139], v[160:163], v[120:123]
	v_mfma_f32_16x16x32_bf16 v[120:123], v[140:143], v[164:167], v[120:123]
	s_setprio 0
	s_setprio 1
	v_mfma_f32_16x16x32_bf16 v[116:119], v[144:147], v[160:163], v[116:119]
	v_mfma_f32_16x16x32_bf16 v[116:119], v[148:151], v[164:167], v[116:119]
	v_mfma_f32_16x16x32_bf16 v[100:103], v[144:147], v[168:171], v[100:103]
	v_mfma_f32_16x16x32_bf16 v[100:103], v[148:151], v[172:175], v[100:103]
	v_mfma_f32_16x16x32_bf16 v[84:87], v[144:147], v[192:195], v[84:87]
	v_mfma_f32_16x16x32_bf16 v[84:87], v[148:151], v[196:199], v[84:87]
	v_mfma_f32_16x16x32_bf16 v[68:71], v[144:147], v[200:203], v[68:71]
	v_mfma_f32_16x16x32_bf16 v[68:71], v[148:151], v[212:215], v[68:71]
	v_mfma_f32_16x16x32_bf16 v[64:67], v[152:155], v[200:203], v[64:67]
	v_mfma_f32_16x16x32_bf16 v[64:67], v[156:159], v[212:215], v[64:67]
	v_mfma_f32_16x16x32_bf16 v[80:83], v[152:155], v[192:195], v[80:83]
	v_mfma_f32_16x16x32_bf16 v[80:83], v[156:159], v[196:199], v[80:83]
	v_mfma_f32_16x16x32_bf16 v[96:99], v[152:155], v[168:171], v[96:99]
	v_mfma_f32_16x16x32_bf16 v[96:99], v[156:159], v[172:175], v[96:99]
	v_mfma_f32_16x16x32_bf16 v[112:115], v[152:155], v[160:163], v[112:115]
	v_mfma_f32_16x16x32_bf16 v[112:115], v[156:159], v[164:167], v[112:115]
	s_setprio 0
	s_barrier
	s_add_i32 s20, s83, s62
	v_lshl_add_u64 v[216:217], s[58:59], 0, v[178:179]
	s_mov_b32 m0, s20
	ds_read_b128 v[160:163], v209 offset:16384
	ds_read_b128 v[164:167], v209 offset:17408
	ds_read_b128 v[168:171], v209 offset:18432
	ds_read_b128 v[172:175], v209 offset:19456
	ds_read_b128 v[192:195], v209 offset:20480
	ds_read_b128 v[196:199], v209 offset:21504
	ds_read_b128 v[200:203], v209 offset:22528
	ds_read_b128 v[212:215], v209 offset:23552
	global_load_lds_dwordx4 v[216:217], off
	s_add_i32 m0, s20, 0x2000
	s_add_u32 s20, s58, 0xb0000
	v_lshl_add_u64 v[218:219], s[58:59], 0, v[182:183]
	s_addc_u32 s21, s59, 0
	s_add_i32 s33, s84, s62
	global_load_lds_dwordx4 v[218:219], off
	v_lshl_add_u64 v[220:221], s[20:21], 0, v[178:179]
	s_mov_b32 m0, s33
	v_lshl_add_u64 v[222:223], s[60:61], 0, v[180:181]
	global_load_lds_dwordx4 v[220:221], off
	v_lshl_add_u64 v[220:221], s[20:21], 0, v[182:183]
	s_add_i32 m0, s33, 0x2000
	s_nop 0
	global_load_lds_dwordx4 v[220:221], off
	v_lshl_add_u64 v[220:221], s[60:61], 0, v[176:177]
	s_mov_b32 m0, s63
	s_nop 0
	global_load_lds_dwordx4 v[220:221], off
	s_mov_b32 m0, s64
	s_nop 0
	global_load_lds_dwordx4 v[222:223], off
	s_waitcnt vmcnt(8)
	s_waitcnt lgkmcnt(0)
	s_barrier
	s_setprio 1
	s_waitcnt lgkmcnt(0)
	v_mfma_f32_16x16x32_bf16 v[60:63], v[128:131], v[160:163], v[60:63]
	v_mfma_f32_16x16x32_bf16 v[60:63], v[132:135], v[164:167], v[60:63]
	v_mfma_f32_16x16x32_bf16 v[44:47], v[128:131], v[168:171], v[44:47]
	v_mfma_f32_16x16x32_bf16 v[44:47], v[132:135], v[172:175], v[44:47]
	v_mfma_f32_16x16x32_bf16 v[28:31], v[128:131], v[192:195], v[28:31]
	v_mfma_f32_16x16x32_bf16 v[28:31], v[132:135], v[196:199], v[28:31]
	v_mfma_f32_16x16x32_bf16 v[12:15], v[128:131], v[200:203], v[12:15]
	v_mfma_f32_16x16x32_bf16 v[12:15], v[132:135], v[212:215], v[12:15]
	v_mfma_f32_16x16x32_bf16 v[8:11], v[136:139], v[200:203], v[8:11]
	v_mfma_f32_16x16x32_bf16 v[8:11], v[140:143], v[212:215], v[8:11]
	v_mfma_f32_16x16x32_bf16 v[24:27], v[136:139], v[192:195], v[24:27]
	v_mfma_f32_16x16x32_bf16 v[24:27], v[140:143], v[196:199], v[24:27]
	v_mfma_f32_16x16x32_bf16 v[40:43], v[136:139], v[168:171], v[40:43]
	v_mfma_f32_16x16x32_bf16 v[40:43], v[140:143], v[172:175], v[40:43]
	v_mfma_f32_16x16x32_bf16 v[56:59], v[136:139], v[160:163], v[56:59]
	v_mfma_f32_16x16x32_bf16 v[56:59], v[140:143], v[164:167], v[56:59]
	s_setprio 0
	s_setprio 1
	v_mfma_f32_16x16x32_bf16 v[52:55], v[144:147], v[160:163], v[52:55]
	v_mfma_f32_16x16x32_bf16 v[52:55], v[148:151], v[164:167], v[52:55]
	v_mfma_f32_16x16x32_bf16 v[36:39], v[144:147], v[168:171], v[36:39]
	v_mfma_f32_16x16x32_bf16 v[36:39], v[148:151], v[172:175], v[36:39]
	v_mfma_f32_16x16x32_bf16 v[20:23], v[144:147], v[192:195], v[20:23]
	v_mfma_f32_16x16x32_bf16 v[20:23], v[148:151], v[196:199], v[20:23]
	v_mfma_f32_16x16x32_bf16 v[4:7], v[144:147], v[200:203], v[4:7]
	v_mfma_f32_16x16x32_bf16 v[4:7], v[148:151], v[212:215], v[4:7]
	v_mfma_f32_16x16x32_bf16 v[0:3], v[152:155], v[200:203], v[0:3]
	v_mfma_f32_16x16x32_bf16 v[0:3], v[156:159], v[212:215], v[0:3]
	v_mfma_f32_16x16x32_bf16 v[16:19], v[152:155], v[192:195], v[16:19]
	v_mfma_f32_16x16x32_bf16 v[16:19], v[156:159], v[196:199], v[16:19]
	v_mfma_f32_16x16x32_bf16 v[32:35], v[152:155], v[168:171], v[32:35]
	v_mfma_f32_16x16x32_bf16 v[32:35], v[156:159], v[172:175], v[32:35]
	v_mfma_f32_16x16x32_bf16 v[48:51], v[152:155], v[160:163], v[48:51]
	v_mfma_f32_16x16x32_bf16 v[48:51], v[156:159], v[164:167], v[48:51]
	s_setprio 0
	s_barrier
	s_add_i32 s33, 0, 0x18000
	s_add_i32 s54, 0, 0x1c000
	v_add_u32_e32 v140, s33, v205
	v_add_u32_e32 v156, s54, v205
	ds_read_b128 v[128:131], v140
	ds_read_b128 v[132:135], v140 offset:1024
	ds_read_b128 v[136:139], v140 offset:2048
	ds_read_b128 v[140:143], v140 offset:3072
	ds_read_b128 v[144:147], v156
	ds_read_b128 v[148:151], v156 offset:1024
	ds_read_b128 v[152:155], v156 offset:2048
	ds_read_b128 v[156:159], v156 offset:3072
	s_add_u32 s20, s60, 0xb0000
	s_addc_u32 s21, s61, 0
	s_mov_b32 m0, s65
	v_lshl_add_u64 v[224:225], s[20:21], 0, v[176:177]
	ds_read_b128 v[160:163], v209 offset:32768
	ds_read_b128 v[164:167], v209 offset:33792
	ds_read_b128 v[168:171], v209 offset:34816
	ds_read_b128 v[172:175], v209 offset:35840
	ds_read_b128 v[192:195], v209 offset:36864
	ds_read_b128 v[196:199], v209 offset:37888
	ds_read_b128 v[200:203], v209 offset:38912
	ds_read_b128 v[212:215], v209 offset:39936
	global_load_lds_dwordx4 v[224:225], off
	v_lshl_add_u64 v[224:225], s[20:21], 0, v[180:181]
	s_mov_b32 m0, s76
	s_nop 0
	global_load_lds_dwordx4 v[224:225], off
	s_waitcnt vmcnt(8)
	s_waitcnt lgkmcnt(0)
	s_barrier
	s_setprio 1
	s_waitcnt lgkmcnt(0)
	v_mfma_f32_16x16x32_bf16 v[124:127], v[128:131], v[160:163], v[124:127]
	v_mfma_f32_16x16x32_bf16 v[124:127], v[132:135], v[164:167], v[124:127]
	v_mfma_f32_16x16x32_bf16 v[108:111], v[128:131], v[168:171], v[108:111]
	v_mfma_f32_16x16x32_bf16 v[108:111], v[132:135], v[172:175], v[108:111]
	v_mfma_f32_16x16x32_bf16 v[92:95], v[128:131], v[192:195], v[92:95]
	v_mfma_f32_16x16x32_bf16 v[92:95], v[132:135], v[196:199], v[92:95]
	v_mfma_f32_16x16x32_bf16 v[76:79], v[128:131], v[200:203], v[76:79]
	v_mfma_f32_16x16x32_bf16 v[76:79], v[132:135], v[212:215], v[76:79]
	v_mfma_f32_16x16x32_bf16 v[72:75], v[136:139], v[200:203], v[72:75]
	v_mfma_f32_16x16x32_bf16 v[72:75], v[140:143], v[212:215], v[72:75]
	v_mfma_f32_16x16x32_bf16 v[88:91], v[136:139], v[192:195], v[88:91]
	v_mfma_f32_16x16x32_bf16 v[88:91], v[140:143], v[196:199], v[88:91]
	v_mfma_f32_16x16x32_bf16 v[104:107], v[136:139], v[168:171], v[104:107]
	v_mfma_f32_16x16x32_bf16 v[104:107], v[140:143], v[172:175], v[104:107]
	v_mfma_f32_16x16x32_bf16 v[120:123], v[136:139], v[160:163], v[120:123]
	v_mfma_f32_16x16x32_bf16 v[120:123], v[140:143], v[164:167], v[120:123]
	s_setprio 0
	s_setprio 1
	v_mfma_f32_16x16x32_bf16 v[116:119], v[144:147], v[160:163], v[116:119]
	v_mfma_f32_16x16x32_bf16 v[116:119], v[148:151], v[164:167], v[116:119]
	v_mfma_f32_16x16x32_bf16 v[100:103], v[144:147], v[168:171], v[100:103]
	v_mfma_f32_16x16x32_bf16 v[100:103], v[148:151], v[172:175], v[100:103]
	v_mfma_f32_16x16x32_bf16 v[84:87], v[144:147], v[192:195], v[84:87]
	v_mfma_f32_16x16x32_bf16 v[84:87], v[148:151], v[196:199], v[84:87]
	v_mfma_f32_16x16x32_bf16 v[68:71], v[144:147], v[200:203], v[68:71]
	v_mfma_f32_16x16x32_bf16 v[68:71], v[148:151], v[212:215], v[68:71]
	v_mfma_f32_16x16x32_bf16 v[64:67], v[152:155], v[200:203], v[64:67]
	v_mfma_f32_16x16x32_bf16 v[64:67], v[156:159], v[212:215], v[64:67]
	v_mfma_f32_16x16x32_bf16 v[80:83], v[152:155], v[192:195], v[80:83]
	v_mfma_f32_16x16x32_bf16 v[80:83], v[156:159], v[196:199], v[80:83]
	v_mfma_f32_16x16x32_bf16 v[96:99], v[152:155], v[168:171], v[96:99]
	v_mfma_f32_16x16x32_bf16 v[96:99], v[156:159], v[172:175], v[96:99]
	v_mfma_f32_16x16x32_bf16 v[112:115], v[152:155], v[160:163], v[112:115]
	v_mfma_f32_16x16x32_bf16 v[112:115], v[156:159], v[164:167], v[112:115]
	s_setprio 0
	s_barrier
	s_add_i32 s20, s33, s62
	v_lshl_add_u64 v[216:217], v[216:217], 0, s[18:19]
	s_mov_b32 m0, s20
	ds_read_b128 v[160:163], v209 offset:49152
	ds_read_b128 v[164:167], v209 offset:50176
	ds_read_b128 v[168:171], v209 offset:51200
	ds_read_b128 v[172:175], v209 offset:52224
	ds_read_b128 v[192:195], v209 offset:53248
	ds_read_b128 v[196:199], v209 offset:54272
	ds_read_b128 v[200:203], v209 offset:55296
	ds_read_b128 v[212:215], v209 offset:56320
	global_load_lds_dwordx4 v[216:217], off
	s_add_i32 m0, s20, 0x2000
	s_add_u32 s20, s58, 0xb0080
	v_lshl_add_u64 v[216:217], v[218:219], 0, s[18:19]
	s_addc_u32 s21, s59, 0
	s_add_i32 s33, s54, s62
	global_load_lds_dwordx4 v[216:217], off
	v_lshl_add_u64 v[216:217], s[20:21], 0, v[178:179]
	s_mov_b32 m0, s33
	s_nop 0
	global_load_lds_dwordx4 v[216:217], off
	v_lshl_add_u64 v[216:217], s[20:21], 0, v[182:183]
	s_add_i32 m0, s33, 0x2000
	s_nop 0
	global_load_lds_dwordx4 v[216:217], off
	v_lshl_add_u64 v[216:217], v[220:221], 0, s[18:19]
	s_mov_b32 m0, s78
	s_nop 0
	global_load_lds_dwordx4 v[216:217], off
	v_lshl_add_u64 v[216:217], v[222:223], 0, s[18:19]
	s_mov_b32 m0, s79
	s_nop 0
	global_load_lds_dwordx4 v[216:217], off
	s_waitcnt vmcnt(8)
	s_waitcnt lgkmcnt(0)
	s_barrier
	s_setprio 1
	s_waitcnt lgkmcnt(0)
	v_mfma_f32_16x16x32_bf16 v[60:63], v[128:131], v[160:163], v[60:63]
	v_mfma_f32_16x16x32_bf16 v[60:63], v[132:135], v[164:167], v[60:63]
	v_mfma_f32_16x16x32_bf16 v[44:47], v[128:131], v[168:171], v[44:47]
	v_mfma_f32_16x16x32_bf16 v[44:47], v[132:135], v[172:175], v[44:47]
	v_mfma_f32_16x16x32_bf16 v[28:31], v[128:131], v[192:195], v[28:31]
	v_mfma_f32_16x16x32_bf16 v[28:31], v[132:135], v[196:199], v[28:31]
	v_mfma_f32_16x16x32_bf16 v[12:15], v[128:131], v[200:203], v[12:15]
	v_mfma_f32_16x16x32_bf16 v[12:15], v[132:135], v[212:215], v[12:15]
	v_mfma_f32_16x16x32_bf16 v[8:11], v[136:139], v[200:203], v[8:11]
	v_mfma_f32_16x16x32_bf16 v[8:11], v[140:143], v[212:215], v[8:11]
	v_mfma_f32_16x16x32_bf16 v[24:27], v[136:139], v[192:195], v[24:27]
	v_mfma_f32_16x16x32_bf16 v[24:27], v[140:143], v[196:199], v[24:27]
	v_mfma_f32_16x16x32_bf16 v[40:43], v[136:139], v[168:171], v[40:43]
	v_mfma_f32_16x16x32_bf16 v[40:43], v[140:143], v[172:175], v[40:43]
	v_mfma_f32_16x16x32_bf16 v[56:59], v[136:139], v[160:163], v[56:59]
	v_mfma_f32_16x16x32_bf16 v[56:59], v[140:143], v[164:167], v[56:59]
	s_setprio 0
	s_setprio 1
	v_mfma_f32_16x16x32_bf16 v[52:55], v[144:147], v[160:163], v[52:55]
	v_mfma_f32_16x16x32_bf16 v[52:55], v[148:151], v[164:167], v[52:55]
	v_mfma_f32_16x16x32_bf16 v[36:39], v[144:147], v[168:171], v[36:39]
	v_mfma_f32_16x16x32_bf16 v[36:39], v[148:151], v[172:175], v[36:39]
	v_mfma_f32_16x16x32_bf16 v[20:23], v[144:147], v[192:195], v[20:23]
	v_mfma_f32_16x16x32_bf16 v[20:23], v[148:151], v[196:199], v[20:23]
	v_mfma_f32_16x16x32_bf16 v[4:7], v[144:147], v[200:203], v[4:7]
	v_mfma_f32_16x16x32_bf16 v[4:7], v[148:151], v[212:215], v[4:7]
	v_mfma_f32_16x16x32_bf16 v[0:3], v[152:155], v[200:203], v[0:3]
	v_mfma_f32_16x16x32_bf16 v[0:3], v[156:159], v[212:215], v[0:3]
	v_mfma_f32_16x16x32_bf16 v[16:19], v[152:155], v[192:195], v[16:19]
	v_mfma_f32_16x16x32_bf16 v[16:19], v[156:159], v[196:199], v[16:19]
	v_mfma_f32_16x16x32_bf16 v[32:35], v[152:155], v[168:171], v[32:35]
	v_mfma_f32_16x16x32_bf16 v[32:35], v[156:159], v[172:175], v[32:35]
	v_mfma_f32_16x16x32_bf16 v[48:51], v[152:155], v[160:163], v[48:51]
	v_mfma_f32_16x16x32_bf16 v[48:51], v[156:159], v[164:167], v[48:51]
	s_setprio 0
	s_barrier
	s_add_i32 s91, s91, 2
	s_add_u32 s89, s89, 0x100
	s_addc_u32 s90, s90, 0
	s_cmp_gt_u32 s91, 41
	s_mov_b64 s[54:55], s[56:57]
	s_cbranch_scc0 .LBB0_201
	s_and_b64 vcc, exec, s[48:49]
	s_cbranch_vccz .LBB0_204
	s_barrier

.LBB0_287:
	ds_read_b128 v[128:131], v177
	ds_read_b128 v[132:135], v177 offset:1024
	ds_read_b128 v[164:167], v177 offset:2048
	ds_read_b128 v[194:197], v177 offset:3072
	ds_read_b128 v[198:201], v181
	ds_read_b128 v[202:205], v181 offset:1024
	ds_read_b128 v[206:209], v181 offset:2048
	ds_read_b128 v[214:217], v181 offset:3072
	s_add_u32 s20, s58, 0xfffc0080
	s_addc_u32 s21, s59, -1
	s_cmp_eq_u32 s97, 12
	s_cselect_b32 s63, s7, s21
	s_cselect_b32 s62, s19, s20
	s_cselect_b32 s61, s17, s96
	s_cselect_b32 s60, s57, s95
	v_lshl_add_u64 v[170:171], s[58:59], 0, v[156:157]
	s_add_i32 m0, s65, 0xc000
	ds_read_b128 v[218:221], v185
	ds_read_b128 v[222:225], v185 offset:1024
	ds_read_b128 v[226:229], v185 offset:2048
	ds_read_b128 v[230:233], v185 offset:3072
	ds_read_b128 v[234:237], v185 offset:4096
	ds_read_b128 v[238:241], v185 offset:5120
	ds_read_b128 v[244:247], v185 offset:6144
	ds_read_b128 v[248:251], v185 offset:7168
	global_load_lds_dwordx4 v[170:171], off
	v_lshl_add_u64 v[170:171], s[58:59], 0, v[158:159]
	s_add_i32 m0, s65, 0xe000
	s_nop 0
	global_load_lds_dwordx4 v[170:171], off
	s_waitcnt vmcnt(8)
	s_waitcnt lgkmcnt(0)
	s_barrier
	s_setprio 1
	s_waitcnt lgkmcnt(0)
	v_mfma_f32_16x16x32_bf16 v[124:127], v[128:131], v[218:221], v[124:127]
	v_mfma_f32_16x16x32_bf16 v[124:127], v[132:135], v[222:225], v[124:127]
	v_mfma_f32_16x16x32_bf16 v[108:111], v[128:131], v[226:229], v[108:111]
	v_mfma_f32_16x16x32_bf16 v[108:111], v[132:135], v[230:233], v[108:111]
	v_mfma_f32_16x16x32_bf16 v[92:95], v[128:131], v[234:237], v[92:95]
	v_mfma_f32_16x16x32_bf16 v[92:95], v[132:135], v[238:241], v[92:95]
	v_mfma_f32_16x16x32_bf16 v[76:79], v[128:131], v[244:247], v[76:79]
	v_mfma_f32_16x16x32_bf16 v[76:79], v[132:135], v[248:251], v[76:79]
	v_mfma_f32_16x16x32_bf16 v[72:75], v[164:167], v[244:247], v[72:75]
	v_mfma_f32_16x16x32_bf16 v[72:75], v[194:197], v[248:251], v[72:75]
	v_mfma_f32_16x16x32_bf16 v[88:91], v[164:167], v[234:237], v[88:91]
	v_mfma_f32_16x16x32_bf16 v[88:91], v[194:197], v[238:241], v[88:91]
	v_mfma_f32_16x16x32_bf16 v[104:107], v[164:167], v[226:229], v[104:107]
	v_mfma_f32_16x16x32_bf16 v[104:107], v[194:197], v[230:233], v[104:107]
	v_mfma_f32_16x16x32_bf16 v[120:123], v[164:167], v[218:221], v[120:123]
	v_mfma_f32_16x16x32_bf16 v[120:123], v[194:197], v[222:225], v[120:123]
	s_setprio 0
	s_setprio 1
	v_mfma_f32_16x16x32_bf16 v[116:119], v[198:201], v[218:221], v[116:119]
	v_mfma_f32_16x16x32_bf16 v[116:119], v[202:205], v[222:225], v[116:119]
	v_mfma_f32_16x16x32_bf16 v[100:103], v[198:201], v[226:229], v[100:103]
	v_mfma_f32_16x16x32_bf16 v[100:103], v[202:205], v[230:233], v[100:103]
	v_mfma_f32_16x16x32_bf16 v[84:87], v[198:201], v[234:237], v[84:87]
	v_mfma_f32_16x16x32_bf16 v[84:87], v[202:205], v[238:241], v[84:87]
	v_mfma_f32_16x16x32_bf16 v[68:71], v[198:201], v[244:247], v[68:71]
	v_mfma_f32_16x16x32_bf16 v[68:71], v[202:205], v[248:251], v[68:71]
	v_mfma_f32_16x16x32_bf16 v[64:67], v[206:209], v[244:247], v[64:67]
	v_mfma_f32_16x16x32_bf16 v[64:67], v[214:217], v[248:251], v[64:67]
	v_mfma_f32_16x16x32_bf16 v[80:83], v[206:209], v[234:237], v[80:83]
	v_mfma_f32_16x16x32_bf16 v[80:83], v[214:217], v[238:241], v[80:83]
	v_mfma_f32_16x16x32_bf16 v[96:99], v[206:209], v[226:229], v[96:99]
	v_mfma_f32_16x16x32_bf16 v[96:99], v[214:217], v[230:233], v[96:99]
	v_mfma_f32_16x16x32_bf16 v[112:115], v[206:209], v[218:221], v[112:115]
	v_mfma_f32_16x16x32_bf16 v[112:115], v[214:217], v[222:225], v[112:115]
	s_setprio 0
	s_barrier
	s_add_i32 s20, s89, s64
	v_lshl_add_u64 v[170:171], s[60:61], 0, v[138:139]
	s_mov_b32 m0, s20
	ds_read_b128 v[218:221], v185 offset:16384
	ds_read_b128 v[222:225], v185 offset:17408
	ds_read_b128 v[226:229], v185 offset:18432
	ds_read_b128 v[230:233], v185 offset:19456
	ds_read_b128 v[234:237], v185 offset:20480
	ds_read_b128 v[238:241], v185 offset:21504
	ds_read_b128 v[244:247], v185 offset:22528
	ds_read_b128 v[248:251], v185 offset:23552
	global_load_lds_dwordx4 v[170:171], off
	s_add_i32 m0, s20, 0x2000
	s_add_u32 s20, s60, 0x40000
	v_lshl_add_u64 v[174:175], s[60:61], 0, v[142:143]
	s_addc_u32 s21, s61, 0
	s_add_i32 s33, s90, s64
	global_load_lds_dwordx4 v[174:175], off
	v_lshl_add_u64 v[178:179], s[20:21], 0, v[138:139]
	s_mov_b32 m0, s33
	v_lshl_add_u64 v[182:183], s[62:63], 0, v[140:141]
	global_load_lds_dwordx4 v[178:179], off
	v_lshl_add_u64 v[178:179], s[20:21], 0, v[142:143]
	s_add_i32 m0, s33, 0x2000
	s_nop 0
	global_load_lds_dwordx4 v[178:179], off
	v_lshl_add_u64 v[178:179], s[62:63], 0, v[136:137]
	s_mov_b32 m0, s65
	s_nop 0
	global_load_lds_dwordx4 v[178:179], off
	s_mov_b32 m0, s76
	s_nop 0
	global_load_lds_dwordx4 v[182:183], off
	s_waitcnt vmcnt(8)
	s_waitcnt lgkmcnt(0)
	s_barrier
	s_setprio 1
	s_waitcnt lgkmcnt(0)
	v_mfma_f32_16x16x32_bf16 v[60:63], v[128:131], v[218:221], v[60:63]
	v_mfma_f32_16x16x32_bf16 v[60:63], v[132:135], v[222:225], v[60:63]
	v_mfma_f32_16x16x32_bf16 v[44:47], v[128:131], v[226:229], v[44:47]
	v_mfma_f32_16x16x32_bf16 v[44:47], v[132:135], v[230:233], v[44:47]
	v_mfma_f32_16x16x32_bf16 v[28:31], v[128:131], v[234:237], v[28:31]
	v_mfma_f32_16x16x32_bf16 v[28:31], v[132:135], v[238:241], v[28:31]
	v_mfma_f32_16x16x32_bf16 v[12:15], v[128:131], v[244:247], v[12:15]
	v_mfma_f32_16x16x32_bf16 v[12:15], v[132:135], v[248:251], v[12:15]
	v_mfma_f32_16x16x32_bf16 v[8:11], v[164:167], v[244:247], v[8:11]
	v_mfma_f32_16x16x32_bf16 v[8:11], v[194:197], v[248:251], v[8:11]
	v_mfma_f32_16x16x32_bf16 v[24:27], v[164:167], v[234:237], v[24:27]
	v_mfma_f32_16x16x32_bf16 v[24:27], v[194:197], v[238:241], v[24:27]
	v_mfma_f32_16x16x32_bf16 v[40:43], v[164:167], v[226:229], v[40:43]
	v_mfma_f32_16x16x32_bf16 v[40:43], v[194:197], v[230:233], v[40:43]
	v_mfma_f32_16x16x32_bf16 v[56:59], v[164:167], v[218:221], v[56:59]
	v_mfma_f32_16x16x32_bf16 v[56:59], v[194:197], v[222:225], v[56:59]
	s_setprio 0
	s_setprio 1
	v_mfma_f32_16x16x32_bf16 v[52:55], v[198:201], v[218:221], v[52:55]
	v_mfma_f32_16x16x32_bf16 v[52:55], v[202:205], v[222:225], v[52:55]
	v_mfma_f32_16x16x32_bf16 v[36:39], v[198:201], v[226:229], v[36:39]
	v_mfma_f32_16x16x32_bf16 v[36:39], v[202:205], v[230:233], v[36:39]
	v_mfma_f32_16x16x32_bf16 v[20:23], v[198:201], v[234:237], v[20:23]
	v_mfma_f32_16x16x32_bf16 v[20:23], v[202:205], v[238:241], v[20:23]
	v_mfma_f32_16x16x32_bf16 v[4:7], v[198:201], v[244:247], v[4:7]
	v_mfma_f32_16x16x32_bf16 v[4:7], v[202:205], v[248:251], v[4:7]
	v_mfma_f32_16x16x32_bf16 v[0:3], v[206:209], v[244:247], v[0:3]
	v_mfma_f32_16x16x32_bf16 v[0:3], v[214:217], v[248:251], v[0:3]
	v_mfma_f32_16x16x32_bf16 v[16:19], v[206:209], v[234:237], v[16:19]
	v_mfma_f32_16x16x32_bf16 v[16:19], v[214:217], v[238:241], v[16:19]
	v_mfma_f32_16x16x32_bf16 v[32:35], v[206:209], v[226:229], v[32:35]
	v_mfma_f32_16x16x32_bf16 v[32:35], v[214:217], v[230:233], v[32:35]
	v_mfma_f32_16x16x32_bf16 v[48:51], v[206:209], v[218:221], v[48:51]
	v_mfma_f32_16x16x32_bf16 v[48:51], v[214:217], v[222:225], v[48:51]
	s_setprio 0
	s_barrier
	s_add_i32 s33, 0, 0x18000
	v_add_u32_e32 v144, s33, v169
	s_add_i32 s75, 0, 0x1c000
	ds_read_b128 v[128:131], v144
	ds_read_b128 v[132:135], v144 offset:1024
	ds_read_b128 v[164:167], v144 offset:2048
	ds_read_b128 v[194:197], v144 offset:3072
	v_add_u32_e32 v144, s75, v169
	ds_read_b128 v[198:201], v144
	ds_read_b128 v[202:205], v144 offset:1024
	ds_read_b128 v[206:209], v144 offset:2048
	ds_read_b128 v[214:217], v144 offset:3072
	s_add_u32 s20, s62, 0x40000
	s_addc_u32 s21, s63, 0
	s_mov_b32 m0, s77
	v_lshl_add_u64 v[186:187], s[20:21], 0, v[136:137]
	ds_read_b128 v[218:221], v185 offset:32768
	ds_read_b128 v[222:225], v185 offset:33792
	ds_read_b128 v[226:229], v185 offset:34816
	ds_read_b128 v[230:233], v185 offset:35840
	ds_read_b128 v[234:237], v185 offset:36864
	ds_read_b128 v[238:241], v185 offset:37888
	ds_read_b128 v[244:247], v185 offset:38912
	ds_read_b128 v[248:251], v185 offset:39936
	global_load_lds_dwordx4 v[186:187], off
	v_lshl_add_u64 v[186:187], s[20:21], 0, v[140:141]
	s_mov_b32 m0, s78
	s_nop 0
	global_load_lds_dwordx4 v[186:187], off
	s_waitcnt vmcnt(8)
	s_waitcnt lgkmcnt(0)
	s_barrier
	s_setprio 1
	s_waitcnt lgkmcnt(0)
	v_mfma_f32_16x16x32_bf16 v[124:127], v[128:131], v[218:221], v[124:127]
	v_mfma_f32_16x16x32_bf16 v[124:127], v[132:135], v[222:225], v[124:127]
	v_mfma_f32_16x16x32_bf16 v[108:111], v[128:131], v[226:229], v[108:111]
	v_mfma_f32_16x16x32_bf16 v[108:111], v[132:135], v[230:233], v[108:111]
	v_mfma_f32_16x16x32_bf16 v[92:95], v[128:131], v[234:237], v[92:95]
	v_mfma_f32_16x16x32_bf16 v[92:95], v[132:135], v[238:241], v[92:95]
	v_mfma_f32_16x16x32_bf16 v[76:79], v[128:131], v[244:247], v[76:79]
	v_mfma_f32_16x16x32_bf16 v[76:79], v[132:135], v[248:251], v[76:79]
	v_mfma_f32_16x16x32_bf16 v[72:75], v[164:167], v[244:247], v[72:75]
	v_mfma_f32_16x16x32_bf16 v[72:75], v[194:197], v[248:251], v[72:75]
	v_mfma_f32_16x16x32_bf16 v[88:91], v[164:167], v[234:237], v[88:91]
	v_mfma_f32_16x16x32_bf16 v[88:91], v[194:197], v[238:241], v[88:91]
	v_mfma_f32_16x16x32_bf16 v[104:107], v[164:167], v[226:229], v[104:107]
	v_mfma_f32_16x16x32_bf16 v[104:107], v[194:197], v[230:233], v[104:107]
	v_mfma_f32_16x16x32_bf16 v[120:123], v[164:167], v[218:221], v[120:123]
	v_mfma_f32_16x16x32_bf16 v[120:123], v[194:197], v[222:225], v[120:123]
	s_setprio 0
	s_setprio 1
	v_mfma_f32_16x16x32_bf16 v[116:119], v[198:201], v[218:221], v[116:119]
	v_mfma_f32_16x16x32_bf16 v[116:119], v[202:205], v[222:225], v[116:119]
	v_mfma_f32_16x16x32_bf16 v[100:103], v[198:201], v[226:229], v[100:103]
	v_mfma_f32_16x16x32_bf16 v[100:103], v[202:205], v[230:233], v[100:103]
	v_mfma_f32_16x16x32_bf16 v[84:87], v[198:201], v[234:237], v[84:87]
	v_mfma_f32_16x16x32_bf16 v[84:87], v[202:205], v[238:241], v[84:87]
	v_mfma_f32_16x16x32_bf16 v[68:71], v[198:201], v[244:247], v[68:71]
	v_mfma_f32_16x16x32_bf16 v[68:71], v[202:205], v[248:251], v[68:71]
	v_mfma_f32_16x16x32_bf16 v[64:67], v[206:209], v[244:247], v[64:67]
	v_mfma_f32_16x16x32_bf16 v[64:67], v[214:217], v[248:251], v[64:67]
	v_mfma_f32_16x16x32_bf16 v[80:83], v[206:209], v[234:237], v[80:83]
	v_mfma_f32_16x16x32_bf16 v[80:83], v[214:217], v[238:241], v[80:83]
	v_mfma_f32_16x16x32_bf16 v[96:99], v[206:209], v[226:229], v[96:99]
	v_mfma_f32_16x16x32_bf16 v[96:99], v[214:217], v[230:233], v[96:99]
	v_mfma_f32_16x16x32_bf16 v[112:115], v[206:209], v[218:221], v[112:115]
	v_mfma_f32_16x16x32_bf16 v[112:115], v[214:217], v[222:225], v[112:115]
	s_setprio 0
	s_barrier
	s_add_i32 s20, s33, s64
	v_lshl_add_u64 v[170:171], v[170:171], 0, s[12:13]
	s_mov_b32 m0, s20
	ds_read_b128 v[218:221], v185 offset:49152
	ds_read_b128 v[222:225], v185 offset:50176
	ds_read_b128 v[226:229], v185 offset:51200
	ds_read_b128 v[230:233], v185 offset:52224
	ds_read_b128 v[234:237], v185 offset:53248
	ds_read_b128 v[238:241], v185 offset:54272
	ds_read_b128 v[244:247], v185 offset:55296
	ds_read_b128 v[248:251], v185 offset:56320
	global_load_lds_dwordx4 v[170:171], off
	s_add_i32 m0, s20, 0x2000
	s_add_u32 s20, s60, 0x40080
	v_lshl_add_u64 v[170:171], v[174:175], 0, s[12:13]
	s_addc_u32 s21, s61, 0
	s_add_i32 s33, s75, s64
	global_load_lds_dwordx4 v[170:171], off
	v_lshl_add_u64 v[170:171], s[20:21], 0, v[138:139]
	s_mov_b32 m0, s33
	s_nop 0
	global_load_lds_dwordx4 v[170:171], off
	v_lshl_add_u64 v[170:171], s[20:21], 0, v[142:143]
	s_add_i32 m0, s33, 0x2000
	s_nop 0
	global_load_lds_dwordx4 v[170:171], off
	v_lshl_add_u64 v[170:171], v[178:179], 0, s[12:13]
	s_mov_b32 m0, s82
	s_nop 0
	global_load_lds_dwordx4 v[170:171], off
	v_lshl_add_u64 v[170:171], v[182:183], 0, s[12:13]
	s_mov_b32 m0, s83
	s_nop 0
	global_load_lds_dwordx4 v[170:171], off
	s_waitcnt vmcnt(8)
	s_waitcnt lgkmcnt(0)
	s_barrier
	s_setprio 1
	s_waitcnt lgkmcnt(0)
	v_mfma_f32_16x16x32_bf16 v[60:63], v[128:131], v[218:221], v[60:63]
	v_mfma_f32_16x16x32_bf16 v[60:63], v[132:135], v[222:225], v[60:63]
	v_mfma_f32_16x16x32_bf16 v[44:47], v[128:131], v[226:229], v[44:47]
	v_mfma_f32_16x16x32_bf16 v[44:47], v[132:135], v[230:233], v[44:47]
	v_mfma_f32_16x16x32_bf16 v[28:31], v[128:131], v[234:237], v[28:31]
	v_mfma_f32_16x16x32_bf16 v[28:31], v[132:135], v[238:241], v[28:31]
	v_mfma_f32_16x16x32_bf16 v[12:15], v[128:131], v[244:247], v[12:15]
	v_mfma_f32_16x16x32_bf16 v[12:15], v[132:135], v[248:251], v[12:15]
	v_mfma_f32_16x16x32_bf16 v[8:11], v[164:167], v[244:247], v[8:11]
	v_mfma_f32_16x16x32_bf16 v[8:11], v[194:197], v[248:251], v[8:11]
	v_mfma_f32_16x16x32_bf16 v[24:27], v[164:167], v[234:237], v[24:27]
	v_mfma_f32_16x16x32_bf16 v[24:27], v[194:197], v[238:241], v[24:27]
	v_mfma_f32_16x16x32_bf16 v[40:43], v[164:167], v[226:229], v[40:43]
	v_mfma_f32_16x16x32_bf16 v[40:43], v[194:197], v[230:233], v[40:43]
	v_mfma_f32_16x16x32_bf16 v[56:59], v[164:167], v[218:221], v[56:59]
	v_mfma_f32_16x16x32_bf16 v[56:59], v[194:197], v[222:225], v[56:59]
	s_setprio 0
	s_setprio 1
	v_mfma_f32_16x16x32_bf16 v[52:55], v[198:201], v[218:221], v[52:55]
	v_mfma_f32_16x16x32_bf16 v[52:55], v[202:205], v[222:225], v[52:55]
	v_mfma_f32_16x16x32_bf16 v[36:39], v[198:201], v[226:229], v[36:39]
	v_mfma_f32_16x16x32_bf16 v[36:39], v[202:205], v[230:233], v[36:39]
	v_mfma_f32_16x16x32_bf16 v[20:23], v[198:201], v[234:237], v[20:23]
	v_mfma_f32_16x16x32_bf16 v[20:23], v[202:205], v[238:241], v[20:23]
	v_mfma_f32_16x16x32_bf16 v[4:7], v[198:201], v[244:247], v[4:7]
	v_mfma_f32_16x16x32_bf16 v[4:7], v[202:205], v[248:251], v[4:7]
	v_mfma_f32_16x16x32_bf16 v[0:3], v[206:209], v[244:247], v[0:3]
	v_mfma_f32_16x16x32_bf16 v[0:3], v[214:217], v[248:251], v[0:3]
	v_mfma_f32_16x16x32_bf16 v[16:19], v[206:209], v[234:237], v[16:19]
	v_mfma_f32_16x16x32_bf16 v[16:19], v[214:217], v[238:241], v[16:19]
	v_mfma_f32_16x16x32_bf16 v[32:35], v[206:209], v[226:229], v[32:35]
	v_mfma_f32_16x16x32_bf16 v[32:35], v[214:217], v[230:233], v[32:35]
	v_mfma_f32_16x16x32_bf16 v[48:51], v[206:209], v[218:221], v[48:51]
	v_mfma_f32_16x16x32_bf16 v[48:51], v[214:217], v[222:225], v[48:51]
	s_setprio 0
	s_barrier
	s_add_i32 s97, s97, 2
	s_add_u32 s58, s58, 0x100
	s_addc_u32 s59, s59, 0
	s_add_u32 s95, s95, 0x100
	s_addc_u32 s96, s96, 0
	s_cmp_gt_u32 s97, 13
	s_cbranch_scc0 .LBB0_287
	s_and_b64 vcc, exec, s[14:15]
	s_cbranch_vccz .LBB0_290
	s_barrier

.LBB0_637:
	ds_read_b128 v[112:115], v247
	ds_read_b128 v[116:119], v247 offset:1024
	ds_read_b128 v[124:127], v247 offset:2048
	ds_read_b128 v[128:131], v247 offset:3072
	ds_read_b128 v[132:135], v248
	ds_read_b128 v[140:143], v248 offset:1024
	ds_read_b128 v[144:147], v248 offset:2048
	ds_read_b128 v[152:155], v248 offset:3072
	s_add_u32 s20, s44, 0xfffc0080
	s_addc_u32 s21, s45, -1
	s_cmp_eq_u32 s75, 12
	s_cselect_b32 s51, s19, s21
	s_cselect_b32 s50, s43, s20
	s_cselect_b32 s49, s17, s74
	s_cselect_b32 s48, s66, s67
	v_lshl_add_u64 v[206:207], s[44:45], 0, v[200:201]
	s_add_i32 m0, s53, 0xc000
	ds_read_b128 v[160:163], v249
	ds_read_b128 v[164:167], v249 offset:1024
	ds_read_b128 v[168:171], v249 offset:2048
	ds_read_b128 v[172:175], v249 offset:3072
	ds_read_b128 v[176:179], v249 offset:4096
	ds_read_b128 v[180:183], v249 offset:5120
	ds_read_b128 v[184:187], v249 offset:6144
	ds_read_b128 v[188:191], v249 offset:7168
	global_load_lds_dwordx4 v[206:207], off
	v_lshl_add_u64 v[206:207], s[44:45], 0, v[202:203]
	s_add_i32 m0, s53, 0xe000
	s_nop 0
	global_load_lds_dwordx4 v[206:207], off
	s_waitcnt vmcnt(8)
	s_waitcnt lgkmcnt(0)
	s_barrier
	s_setprio 1
	s_waitcnt lgkmcnt(0)
	v_mfma_f32_16x16x32_bf16 v[156:159], v[112:115], v[160:163], v[156:159]
	v_mfma_f32_16x16x32_bf16 v[156:159], v[116:119], v[164:167], v[156:159]
	v_mfma_f32_16x16x32_bf16 v[108:111], v[112:115], v[168:171], v[108:111]
	v_mfma_f32_16x16x32_bf16 v[108:111], v[116:119], v[172:175], v[108:111]
	v_mfma_f32_16x16x32_bf16 v[92:95], v[112:115], v[176:179], v[92:95]
	v_mfma_f32_16x16x32_bf16 v[92:95], v[116:119], v[180:183], v[92:95]
	v_mfma_f32_16x16x32_bf16 v[76:79], v[112:115], v[184:187], v[76:79]
	v_mfma_f32_16x16x32_bf16 v[76:79], v[116:119], v[188:191], v[76:79]
	v_mfma_f32_16x16x32_bf16 v[72:75], v[124:127], v[184:187], v[72:75]
	v_mfma_f32_16x16x32_bf16 v[72:75], v[128:131], v[188:191], v[72:75]
	v_mfma_f32_16x16x32_bf16 v[88:91], v[124:127], v[176:179], v[88:91]
	v_mfma_f32_16x16x32_bf16 v[88:91], v[128:131], v[180:183], v[88:91]
	v_mfma_f32_16x16x32_bf16 v[104:107], v[124:127], v[168:171], v[104:107]
	v_mfma_f32_16x16x32_bf16 v[104:107], v[128:131], v[172:175], v[104:107]
	v_mfma_f32_16x16x32_bf16 v[148:151], v[124:127], v[160:163], v[148:151]
	v_mfma_f32_16x16x32_bf16 v[148:151], v[128:131], v[164:167], v[148:151]
	s_setprio 0
	s_setprio 1
	v_mfma_f32_16x16x32_bf16 v[136:139], v[132:135], v[160:163], v[136:139]
	v_mfma_f32_16x16x32_bf16 v[136:139], v[140:143], v[164:167], v[136:139]
	v_mfma_f32_16x16x32_bf16 v[100:103], v[132:135], v[168:171], v[100:103]
	v_mfma_f32_16x16x32_bf16 v[100:103], v[140:143], v[172:175], v[100:103]
	v_mfma_f32_16x16x32_bf16 v[84:87], v[132:135], v[176:179], v[84:87]
	v_mfma_f32_16x16x32_bf16 v[84:87], v[140:143], v[180:183], v[84:87]
	v_mfma_f32_16x16x32_bf16 v[68:71], v[132:135], v[184:187], v[68:71]
	v_mfma_f32_16x16x32_bf16 v[68:71], v[140:143], v[188:191], v[68:71]
	v_mfma_f32_16x16x32_bf16 v[64:67], v[144:147], v[184:187], v[64:67]
	v_mfma_f32_16x16x32_bf16 v[64:67], v[152:155], v[188:191], v[64:67]
	v_mfma_f32_16x16x32_bf16 v[80:83], v[144:147], v[176:179], v[80:83]
	v_mfma_f32_16x16x32_bf16 v[80:83], v[152:155], v[180:183], v[80:83]
	v_mfma_f32_16x16x32_bf16 v[96:99], v[144:147], v[168:171], v[96:99]
	v_mfma_f32_16x16x32_bf16 v[96:99], v[152:155], v[172:175], v[96:99]
	v_mfma_f32_16x16x32_bf16 v[120:123], v[144:147], v[160:163], v[120:123]
	v_mfma_f32_16x16x32_bf16 v[120:123], v[152:155], v[164:167], v[120:123]
	s_setprio 0
	s_barrier
	s_add_i32 s20, s63, s52
	v_lshl_add_u64 v[206:207], s[48:49], 0, v[194:195]
	s_mov_b32 m0, s20
	ds_read_b128 v[160:163], v249 offset:16384
	ds_read_b128 v[164:167], v249 offset:17408
	ds_read_b128 v[168:171], v249 offset:18432
	ds_read_b128 v[172:175], v249 offset:19456
	ds_read_b128 v[176:179], v249 offset:20480
	ds_read_b128 v[180:183], v249 offset:21504
	ds_read_b128 v[184:187], v249 offset:22528
	ds_read_b128 v[188:191], v249 offset:23552
	global_load_lds_dwordx4 v[206:207], off
	s_add_i32 m0, s20, 0x2000
	s_add_u32 s20, s48, 0x40000
	v_lshl_add_u64 v[208:209], s[48:49], 0, v[198:199]
	s_addc_u32 s21, s49, 0
	s_add_i32 s33, s64, s52
	global_load_lds_dwordx4 v[208:209], off
	v_lshl_add_u64 v[210:211], s[20:21], 0, v[194:195]
	s_mov_b32 m0, s33
	v_lshl_add_u64 v[212:213], s[50:51], 0, v[196:197]
	global_load_lds_dwordx4 v[210:211], off
	v_lshl_add_u64 v[210:211], s[20:21], 0, v[198:199]
	s_add_i32 m0, s33, 0x2000
	s_nop 0
	global_load_lds_dwordx4 v[210:211], off
	v_lshl_add_u64 v[210:211], s[50:51], 0, v[192:193]
	s_mov_b32 m0, s53
	s_nop 0
	global_load_lds_dwordx4 v[210:211], off
	s_mov_b32 m0, s54
	s_nop 0
	global_load_lds_dwordx4 v[212:213], off
	s_waitcnt vmcnt(8)
	s_waitcnt lgkmcnt(0)
	s_barrier
	s_setprio 1
	s_waitcnt lgkmcnt(0)
	v_mfma_f32_16x16x32_bf16 v[60:63], v[112:115], v[160:163], v[60:63]
	v_mfma_f32_16x16x32_bf16 v[60:63], v[116:119], v[164:167], v[60:63]
	v_mfma_f32_16x16x32_bf16 v[44:47], v[112:115], v[168:171], v[44:47]
	v_mfma_f32_16x16x32_bf16 v[44:47], v[116:119], v[172:175], v[44:47]
	v_mfma_f32_16x16x32_bf16 v[28:31], v[112:115], v[176:179], v[28:31]
	v_mfma_f32_16x16x32_bf16 v[28:31], v[116:119], v[180:183], v[28:31]
	v_mfma_f32_16x16x32_bf16 v[12:15], v[112:115], v[184:187], v[12:15]
	v_mfma_f32_16x16x32_bf16 v[12:15], v[116:119], v[188:191], v[12:15]
	v_mfma_f32_16x16x32_bf16 v[8:11], v[124:127], v[184:187], v[8:11]
	v_mfma_f32_16x16x32_bf16 v[8:11], v[128:131], v[188:191], v[8:11]
	v_mfma_f32_16x16x32_bf16 v[24:27], v[124:127], v[176:179], v[24:27]
	v_mfma_f32_16x16x32_bf16 v[24:27], v[128:131], v[180:183], v[24:27]
	v_mfma_f32_16x16x32_bf16 v[40:43], v[124:127], v[168:171], v[40:43]
	v_mfma_f32_16x16x32_bf16 v[40:43], v[128:131], v[172:175], v[40:43]
	v_mfma_f32_16x16x32_bf16 v[56:59], v[124:127], v[160:163], v[56:59]
	v_mfma_f32_16x16x32_bf16 v[56:59], v[128:131], v[164:167], v[56:59]
	s_setprio 0
	s_setprio 1
	v_mfma_f32_16x16x32_bf16 v[52:55], v[132:135], v[160:163], v[52:55]
	v_mfma_f32_16x16x32_bf16 v[52:55], v[140:143], v[164:167], v[52:55]
	v_mfma_f32_16x16x32_bf16 v[36:39], v[132:135], v[168:171], v[36:39]
	v_mfma_f32_16x16x32_bf16 v[36:39], v[140:143], v[172:175], v[36:39]
	v_mfma_f32_16x16x32_bf16 v[20:23], v[132:135], v[176:179], v[20:23]
	v_mfma_f32_16x16x32_bf16 v[20:23], v[140:143], v[180:183], v[20:23]
	v_mfma_f32_16x16x32_bf16 v[4:7], v[132:135], v[184:187], v[4:7]
	v_mfma_f32_16x16x32_bf16 v[4:7], v[140:143], v[188:191], v[4:7]
	v_mfma_f32_16x16x32_bf16 v[0:3], v[144:147], v[184:187], v[0:3]
	v_mfma_f32_16x16x32_bf16 v[0:3], v[152:155], v[188:191], v[0:3]
	v_mfma_f32_16x16x32_bf16 v[16:19], v[144:147], v[176:179], v[16:19]
	v_mfma_f32_16x16x32_bf16 v[16:19], v[152:155], v[180:183], v[16:19]
	v_mfma_f32_16x16x32_bf16 v[32:35], v[144:147], v[168:171], v[32:35]
	v_mfma_f32_16x16x32_bf16 v[32:35], v[152:155], v[172:175], v[32:35]
	v_mfma_f32_16x16x32_bf16 v[48:51], v[144:147], v[160:163], v[48:51]
	v_mfma_f32_16x16x32_bf16 v[48:51], v[152:155], v[164:167], v[48:51]
	s_setprio 0
	s_barrier
	s_add_i32 s33, 0, 0x18000
	s_add_i32 s76, 0, 0x1c000
	v_add_u32_e32 v128, s33, v245
	v_add_u32_e32 v152, s76, v245
	ds_read_b128 v[112:115], v128
	ds_read_b128 v[116:119], v128 offset:1024
	ds_read_b128 v[124:127], v128 offset:2048
	ds_read_b128 v[128:131], v128 offset:3072
	ds_read_b128 v[132:135], v152
	ds_read_b128 v[140:143], v152 offset:1024
	ds_read_b128 v[144:147], v152 offset:2048
	ds_read_b128 v[152:155], v152 offset:3072
	s_add_u32 s20, s50, 0x40000
	s_addc_u32 s21, s51, 0
	s_mov_b32 m0, s55
	v_lshl_add_u64 v[214:215], s[20:21], 0, v[192:193]
	ds_read_b128 v[160:163], v249 offset:32768
	ds_read_b128 v[164:167], v249 offset:33792
	ds_read_b128 v[168:171], v249 offset:34816
	ds_read_b128 v[172:175], v249 offset:35840
	ds_read_b128 v[176:179], v249 offset:36864
	ds_read_b128 v[180:183], v249 offset:37888
	ds_read_b128 v[184:187], v249 offset:38912
	ds_read_b128 v[188:191], v249 offset:39936
	global_load_lds_dwordx4 v[214:215], off
	v_lshl_add_u64 v[214:215], s[20:21], 0, v[196:197]
	s_mov_b32 m0, s56
	s_nop 0
	global_load_lds_dwordx4 v[214:215], off
	s_waitcnt vmcnt(8)
	s_waitcnt lgkmcnt(0)
	s_barrier
	s_setprio 1
	s_waitcnt lgkmcnt(0)
	v_mfma_f32_16x16x32_bf16 v[156:159], v[112:115], v[160:163], v[156:159]
	v_mfma_f32_16x16x32_bf16 v[156:159], v[116:119], v[164:167], v[156:159]
	v_mfma_f32_16x16x32_bf16 v[108:111], v[112:115], v[168:171], v[108:111]
	v_mfma_f32_16x16x32_bf16 v[108:111], v[116:119], v[172:175], v[108:111]
	v_mfma_f32_16x16x32_bf16 v[92:95], v[112:115], v[176:179], v[92:95]
	v_mfma_f32_16x16x32_bf16 v[92:95], v[116:119], v[180:183], v[92:95]
	v_mfma_f32_16x16x32_bf16 v[76:79], v[112:115], v[184:187], v[76:79]
	v_mfma_f32_16x16x32_bf16 v[76:79], v[116:119], v[188:191], v[76:79]
	v_mfma_f32_16x16x32_bf16 v[72:75], v[124:127], v[184:187], v[72:75]
	v_mfma_f32_16x16x32_bf16 v[72:75], v[128:131], v[188:191], v[72:75]
	v_mfma_f32_16x16x32_bf16 v[88:91], v[124:127], v[176:179], v[88:91]
	v_mfma_f32_16x16x32_bf16 v[88:91], v[128:131], v[180:183], v[88:91]
	v_mfma_f32_16x16x32_bf16 v[104:107], v[124:127], v[168:171], v[104:107]
	v_mfma_f32_16x16x32_bf16 v[104:107], v[128:131], v[172:175], v[104:107]
	v_mfma_f32_16x16x32_bf16 v[148:151], v[124:127], v[160:163], v[148:151]
	v_mfma_f32_16x16x32_bf16 v[148:151], v[128:131], v[164:167], v[148:151]
	s_setprio 0
	s_setprio 1
	v_mfma_f32_16x16x32_bf16 v[136:139], v[132:135], v[160:163], v[136:139]
	v_mfma_f32_16x16x32_bf16 v[136:139], v[140:143], v[164:167], v[136:139]
	v_mfma_f32_16x16x32_bf16 v[100:103], v[132:135], v[168:171], v[100:103]
	v_mfma_f32_16x16x32_bf16 v[100:103], v[140:143], v[172:175], v[100:103]
	v_mfma_f32_16x16x32_bf16 v[84:87], v[132:135], v[176:179], v[84:87]
	v_mfma_f32_16x16x32_bf16 v[84:87], v[140:143], v[180:183], v[84:87]
	v_mfma_f32_16x16x32_bf16 v[68:71], v[132:135], v[184:187], v[68:71]
	v_mfma_f32_16x16x32_bf16 v[68:71], v[140:143], v[188:191], v[68:71]
	v_mfma_f32_16x16x32_bf16 v[64:67], v[144:147], v[184:187], v[64:67]
	v_mfma_f32_16x16x32_bf16 v[64:67], v[152:155], v[188:191], v[64:67]
	v_mfma_f32_16x16x32_bf16 v[80:83], v[144:147], v[176:179], v[80:83]
	v_mfma_f32_16x16x32_bf16 v[80:83], v[152:155], v[180:183], v[80:83]
	v_mfma_f32_16x16x32_bf16 v[96:99], v[144:147], v[168:171], v[96:99]
	v_mfma_f32_16x16x32_bf16 v[96:99], v[152:155], v[172:175], v[96:99]
	v_mfma_f32_16x16x32_bf16 v[120:123], v[144:147], v[160:163], v[120:123]
	v_mfma_f32_16x16x32_bf16 v[120:123], v[152:155], v[164:167], v[120:123]
	s_setprio 0
	s_barrier
	s_add_i32 s20, s33, s52
	v_lshl_add_u64 v[206:207], v[206:207], 0, s[12:13]
	s_mov_b32 m0, s20
	ds_read_b128 v[160:163], v249 offset:49152
	ds_read_b128 v[164:167], v249 offset:50176
	ds_read_b128 v[168:171], v249 offset:51200
	ds_read_b128 v[172:175], v249 offset:52224
	ds_read_b128 v[176:179], v249 offset:53248
	ds_read_b128 v[180:183], v249 offset:54272
	ds_read_b128 v[184:187], v249 offset:55296
	ds_read_b128 v[188:191], v249 offset:56320
	global_load_lds_dwordx4 v[206:207], off
	s_add_i32 m0, s20, 0x2000
	s_add_u32 s20, s48, 0x40080
	v_lshl_add_u64 v[206:207], v[208:209], 0, s[12:13]
	s_addc_u32 s21, s49, 0
	s_add_i32 s33, s76, s52
	global_load_lds_dwordx4 v[206:207], off
	v_lshl_add_u64 v[206:207], s[20:21], 0, v[194:195]
	s_mov_b32 m0, s33
	s_nop 0
	global_load_lds_dwordx4 v[206:207], off
	v_lshl_add_u64 v[206:207], s[20:21], 0, v[198:199]
	s_add_i32 m0, s33, 0x2000
	s_nop 0
	global_load_lds_dwordx4 v[206:207], off
	v_lshl_add_u64 v[206:207], v[210:211], 0, s[12:13]
	s_mov_b32 m0, s58
	s_nop 0
	global_load_lds_dwordx4 v[206:207], off
	v_lshl_add_u64 v[206:207], v[212:213], 0, s[12:13]
	s_mov_b32 m0, s59
	s_nop 0
	global_load_lds_dwordx4 v[206:207], off
	s_waitcnt vmcnt(8)
	s_waitcnt lgkmcnt(0)
	s_barrier
	s_setprio 1
	s_waitcnt lgkmcnt(0)
	v_mfma_f32_16x16x32_bf16 v[60:63], v[112:115], v[160:163], v[60:63]
	v_mfma_f32_16x16x32_bf16 v[60:63], v[116:119], v[164:167], v[60:63]
	v_mfma_f32_16x16x32_bf16 v[44:47], v[112:115], v[168:171], v[44:47]
	v_mfma_f32_16x16x32_bf16 v[44:47], v[116:119], v[172:175], v[44:47]
	v_mfma_f32_16x16x32_bf16 v[28:31], v[112:115], v[176:179], v[28:31]
	v_mfma_f32_16x16x32_bf16 v[28:31], v[116:119], v[180:183], v[28:31]
	v_mfma_f32_16x16x32_bf16 v[12:15], v[112:115], v[184:187], v[12:15]
	v_mfma_f32_16x16x32_bf16 v[12:15], v[116:119], v[188:191], v[12:15]
	v_mfma_f32_16x16x32_bf16 v[8:11], v[124:127], v[184:187], v[8:11]
	v_mfma_f32_16x16x32_bf16 v[8:11], v[128:131], v[188:191], v[8:11]
	v_mfma_f32_16x16x32_bf16 v[24:27], v[124:127], v[176:179], v[24:27]
	v_mfma_f32_16x16x32_bf16 v[24:27], v[128:131], v[180:183], v[24:27]
	v_mfma_f32_16x16x32_bf16 v[40:43], v[124:127], v[168:171], v[40:43]
	v_mfma_f32_16x16x32_bf16 v[40:43], v[128:131], v[172:175], v[40:43]
	v_mfma_f32_16x16x32_bf16 v[56:59], v[124:127], v[160:163], v[56:59]
	v_mfma_f32_16x16x32_bf16 v[56:59], v[128:131], v[164:167], v[56:59]
	s_setprio 0
	s_setprio 1
	v_mfma_f32_16x16x32_bf16 v[52:55], v[132:135], v[160:163], v[52:55]
	v_mfma_f32_16x16x32_bf16 v[52:55], v[140:143], v[164:167], v[52:55]
	v_mfma_f32_16x16x32_bf16 v[36:39], v[132:135], v[168:171], v[36:39]
	v_mfma_f32_16x16x32_bf16 v[36:39], v[140:143], v[172:175], v[36:39]
	v_mfma_f32_16x16x32_bf16 v[20:23], v[132:135], v[176:179], v[20:23]
	v_mfma_f32_16x16x32_bf16 v[20:23], v[140:143], v[180:183], v[20:23]
	v_mfma_f32_16x16x32_bf16 v[4:7], v[132:135], v[184:187], v[4:7]
	v_mfma_f32_16x16x32_bf16 v[4:7], v[140:143], v[188:191], v[4:7]
	v_mfma_f32_16x16x32_bf16 v[0:3], v[144:147], v[184:187], v[0:3]
	v_mfma_f32_16x16x32_bf16 v[0:3], v[152:155], v[188:191], v[0:3]
	v_mfma_f32_16x16x32_bf16 v[16:19], v[144:147], v[176:179], v[16:19]
	v_mfma_f32_16x16x32_bf16 v[16:19], v[152:155], v[180:183], v[16:19]
	v_mfma_f32_16x16x32_bf16 v[32:35], v[144:147], v[168:171], v[32:35]
	v_mfma_f32_16x16x32_bf16 v[32:35], v[152:155], v[172:175], v[32:35]
	v_mfma_f32_16x16x32_bf16 v[48:51], v[144:147], v[160:163], v[48:51]
	v_mfma_f32_16x16x32_bf16 v[48:51], v[152:155], v[164:167], v[48:51]
	s_setprio 0
	s_barrier
	s_add_i32 s75, s75, 2
	s_add_u32 s44, s44, 0x100
	s_addc_u32 s45, s45, 0
	s_add_u32 s67, s67, 0x100
	s_addc_u32 s74, s74, 0
	s_cmp_gt_u32 s75, 13
	s_cbranch_scc0 .LBB0_637
	s_and_b64 vcc, exec, s[14:15]
	s_cbranch_vccz .LBB0_640
	s_barrier

.LBB0_721:
	ds_read_b128 v[146:149], v163
	ds_read_b128 v[152:155], v163 offset:1024
	ds_read_b128 v[172:175], v163 offset:2048
	ds_read_b128 v[178:181], v163 offset:3072
	ds_read_b128 v[182:185], v167
	ds_read_b128 v[186:189], v167 offset:1024
	ds_read_b128 v[190:193], v167 offset:2048
	ds_read_b128 v[194:197], v167 offset:3072
	s_add_u32 s20, s36, 0xfffc0080
	s_addc_u32 s21, s37, -1
	s_cmp_eq_u32 s61, 12
	s_cselect_b32 s41, s13, s21
	s_cselect_b32 s40, s57, s20
	s_cselect_b32 s39, s1, s60
	s_cselect_b32 s38, s58, s59
	v_lshl_add_u64 v[158:159], s[36:37], 0, v[138:139]
	s_add_i32 m0, s19, 0xc000
	ds_read_b128 v[198:201], v171
	ds_read_b128 v[202:205], v171 offset:1024
	ds_read_b128 v[206:209], v171 offset:2048
	ds_read_b128 v[210:213], v171 offset:3072
	ds_read_b128 v[214:217], v171 offset:4096
	ds_read_b128 v[218:221], v171 offset:5120
	ds_read_b128 v[222:225], v171 offset:6144
	ds_read_b128 v[226:229], v171 offset:7168
	global_load_lds_dwordx4 v[158:159], off
	v_lshl_add_u64 v[158:159], s[36:37], 0, v[140:141]
	s_add_i32 m0, s19, 0xe000
	s_nop 0
	global_load_lds_dwordx4 v[158:159], off
	s_waitcnt vmcnt(8)
	s_waitcnt lgkmcnt(0)
	s_barrier
	s_setprio 1
	s_waitcnt lgkmcnt(0)
	v_mfma_f32_16x16x32_bf16 v[124:127], v[146:149], v[198:201], v[124:127]
	v_mfma_f32_16x16x32_bf16 v[124:127], v[152:155], v[202:205], v[124:127]
	v_mfma_f32_16x16x32_bf16 v[108:111], v[146:149], v[206:209], v[108:111]
	v_mfma_f32_16x16x32_bf16 v[108:111], v[152:155], v[210:213], v[108:111]
	v_mfma_f32_16x16x32_bf16 v[92:95], v[146:149], v[214:217], v[92:95]
	v_mfma_f32_16x16x32_bf16 v[92:95], v[152:155], v[218:221], v[92:95]
	v_mfma_f32_16x16x32_bf16 v[76:79], v[146:149], v[222:225], v[76:79]
	v_mfma_f32_16x16x32_bf16 v[76:79], v[152:155], v[226:229], v[76:79]
	v_mfma_f32_16x16x32_bf16 v[68:71], v[172:175], v[222:225], v[68:71]
	v_mfma_f32_16x16x32_bf16 v[68:71], v[178:181], v[226:229], v[68:71]
	v_mfma_f32_16x16x32_bf16 v[84:87], v[172:175], v[214:217], v[84:87]
	v_mfma_f32_16x16x32_bf16 v[84:87], v[178:181], v[218:221], v[84:87]
	v_mfma_f32_16x16x32_bf16 v[100:103], v[172:175], v[206:209], v[100:103]
	v_mfma_f32_16x16x32_bf16 v[100:103], v[178:181], v[210:213], v[100:103]
	v_mfma_f32_16x16x32_bf16 v[116:119], v[172:175], v[198:201], v[116:119]
	v_mfma_f32_16x16x32_bf16 v[116:119], v[178:181], v[202:205], v[116:119]
	s_setprio 0
	s_setprio 1
	v_mfma_f32_16x16x32_bf16 v[120:123], v[182:185], v[198:201], v[120:123]
	v_mfma_f32_16x16x32_bf16 v[120:123], v[186:189], v[202:205], v[120:123]
	v_mfma_f32_16x16x32_bf16 v[104:107], v[182:185], v[206:209], v[104:107]
	v_mfma_f32_16x16x32_bf16 v[104:107], v[186:189], v[210:213], v[104:107]
	v_mfma_f32_16x16x32_bf16 v[88:91], v[182:185], v[214:217], v[88:91]
	v_mfma_f32_16x16x32_bf16 v[88:91], v[186:189], v[218:221], v[88:91]
	v_mfma_f32_16x16x32_bf16 v[72:75], v[182:185], v[222:225], v[72:75]
	v_mfma_f32_16x16x32_bf16 v[72:75], v[186:189], v[226:229], v[72:75]
	v_mfma_f32_16x16x32_bf16 v[64:67], v[190:193], v[222:225], v[64:67]
	v_mfma_f32_16x16x32_bf16 v[64:67], v[194:197], v[226:229], v[64:67]
	v_mfma_f32_16x16x32_bf16 v[80:83], v[190:193], v[214:217], v[80:83]
	v_mfma_f32_16x16x32_bf16 v[80:83], v[194:197], v[218:221], v[80:83]
	v_mfma_f32_16x16x32_bf16 v[96:99], v[190:193], v[206:209], v[96:99]
	v_mfma_f32_16x16x32_bf16 v[96:99], v[194:197], v[210:213], v[96:99]
	v_mfma_f32_16x16x32_bf16 v[112:115], v[190:193], v[198:201], v[112:115]
	v_mfma_f32_16x16x32_bf16 v[112:115], v[194:197], v[202:205], v[112:115]
	s_setprio 0
	s_barrier
	s_add_i32 s20, s53, s42
	v_lshl_add_u64 v[158:159], s[38:39], 0, v[132:133]
	s_mov_b32 m0, s20
	ds_read_b128 v[198:201], v171 offset:16384
	ds_read_b128 v[202:205], v171 offset:17408
	ds_read_b128 v[206:209], v171 offset:18432
	ds_read_b128 v[210:213], v171 offset:19456
	ds_read_b128 v[214:217], v171 offset:20480
	ds_read_b128 v[218:221], v171 offset:21504
	ds_read_b128 v[222:225], v171 offset:22528
	ds_read_b128 v[226:229], v171 offset:23552
	global_load_lds_dwordx4 v[158:159], off
	s_add_i32 m0, s20, 0x2000
	s_add_u32 s20, s38, 0x40000
	v_lshl_add_u64 v[164:165], s[38:39], 0, v[128:129]
	s_addc_u32 s21, s39, 0
	s_add_i32 s33, s54, s42
	global_load_lds_dwordx4 v[164:165], off
	v_lshl_add_u64 v[168:169], s[20:21], 0, v[132:133]
	s_mov_b32 m0, s33
	v_lshl_add_u64 v[230:231], s[40:41], 0, v[130:131]
	global_load_lds_dwordx4 v[168:169], off
	v_lshl_add_u64 v[168:169], s[20:21], 0, v[128:129]
	s_add_i32 m0, s33, 0x2000
	s_nop 0
	global_load_lds_dwordx4 v[168:169], off
	v_lshl_add_u64 v[168:169], s[40:41], 0, v[134:135]
	s_mov_b32 m0, s19
	s_nop 0
	global_load_lds_dwordx4 v[168:169], off
	s_mov_b32 m0, s45
	s_nop 0
	global_load_lds_dwordx4 v[230:231], off
	s_waitcnt vmcnt(8)
	s_waitcnt lgkmcnt(0)
	s_barrier
	s_setprio 1
	s_waitcnt lgkmcnt(0)
	v_mfma_f32_16x16x32_bf16 v[60:63], v[146:149], v[198:201], v[60:63]
	v_mfma_f32_16x16x32_bf16 v[60:63], v[152:155], v[202:205], v[60:63]
	v_mfma_f32_16x16x32_bf16 v[44:47], v[146:149], v[206:209], v[44:47]
	v_mfma_f32_16x16x32_bf16 v[44:47], v[152:155], v[210:213], v[44:47]
	v_mfma_f32_16x16x32_bf16 v[28:31], v[146:149], v[214:217], v[28:31]
	v_mfma_f32_16x16x32_bf16 v[28:31], v[152:155], v[218:221], v[28:31]
	v_mfma_f32_16x16x32_bf16 v[12:15], v[146:149], v[222:225], v[12:15]
	v_mfma_f32_16x16x32_bf16 v[12:15], v[152:155], v[226:229], v[12:15]
	v_mfma_f32_16x16x32_bf16 v[4:7], v[172:175], v[222:225], v[4:7]
	v_mfma_f32_16x16x32_bf16 v[4:7], v[178:181], v[226:229], v[4:7]
	v_mfma_f32_16x16x32_bf16 v[20:23], v[172:175], v[214:217], v[20:23]
	v_mfma_f32_16x16x32_bf16 v[20:23], v[178:181], v[218:221], v[20:23]
	v_mfma_f32_16x16x32_bf16 v[36:39], v[172:175], v[206:209], v[36:39]
	v_mfma_f32_16x16x32_bf16 v[36:39], v[178:181], v[210:213], v[36:39]
	v_mfma_f32_16x16x32_bf16 v[52:55], v[172:175], v[198:201], v[52:55]
	v_mfma_f32_16x16x32_bf16 v[52:55], v[178:181], v[202:205], v[52:55]
	s_setprio 0
	s_setprio 1
	v_mfma_f32_16x16x32_bf16 v[56:59], v[182:185], v[198:201], v[56:59]
	v_mfma_f32_16x16x32_bf16 v[56:59], v[186:189], v[202:205], v[56:59]
	v_mfma_f32_16x16x32_bf16 v[40:43], v[182:185], v[206:209], v[40:43]
	v_mfma_f32_16x16x32_bf16 v[40:43], v[186:189], v[210:213], v[40:43]
	v_mfma_f32_16x16x32_bf16 v[24:27], v[182:185], v[214:217], v[24:27]
	v_mfma_f32_16x16x32_bf16 v[24:27], v[186:189], v[218:221], v[24:27]
	v_mfma_f32_16x16x32_bf16 v[8:11], v[182:185], v[222:225], v[8:11]
	v_mfma_f32_16x16x32_bf16 v[8:11], v[186:189], v[226:229], v[8:11]
	v_mfma_f32_16x16x32_bf16 v[0:3], v[190:193], v[222:225], v[0:3]
	v_mfma_f32_16x16x32_bf16 v[0:3], v[194:197], v[226:229], v[0:3]
	v_mfma_f32_16x16x32_bf16 v[16:19], v[190:193], v[214:217], v[16:19]
	v_mfma_f32_16x16x32_bf16 v[16:19], v[194:197], v[218:221], v[16:19]
	v_mfma_f32_16x16x32_bf16 v[32:35], v[190:193], v[206:209], v[32:35]
	v_mfma_f32_16x16x32_bf16 v[32:35], v[194:197], v[210:213], v[32:35]
	v_mfma_f32_16x16x32_bf16 v[48:51], v[190:193], v[198:201], v[48:51]
	v_mfma_f32_16x16x32_bf16 v[48:51], v[194:197], v[202:205], v[48:51]
	s_setprio 0
	s_barrier
	s_add_i32 s33, 0, 0x18000
	v_add_u32_e32 v150, s33, v157
	s_add_i32 s62, 0, 0x1c000
	ds_read_b128 v[146:149], v150
	ds_read_b128 v[152:155], v150 offset:1024
	ds_read_b128 v[172:175], v150 offset:2048
	ds_read_b128 v[178:181], v150 offset:3072
	v_add_u32_e32 v150, s62, v157
	ds_read_b128 v[182:185], v150
	ds_read_b128 v[186:189], v150 offset:1024
	ds_read_b128 v[190:193], v150 offset:2048
	ds_read_b128 v[194:197], v150 offset:3072
	s_add_u32 s20, s40, 0x40000
	s_addc_u32 s21, s41, 0
	s_mov_b32 m0, s46
	v_lshl_add_u64 v[232:233], s[20:21], 0, v[134:135]
	ds_read_b128 v[198:201], v171 offset:32768
	ds_read_b128 v[202:205], v171 offset:33792
	ds_read_b128 v[206:209], v171 offset:34816
	ds_read_b128 v[210:213], v171 offset:35840
	ds_read_b128 v[214:217], v171 offset:36864
	ds_read_b128 v[218:221], v171 offset:37888
	ds_read_b128 v[222:225], v171 offset:38912
	ds_read_b128 v[226:229], v171 offset:39936
	global_load_lds_dwordx4 v[232:233], off
	v_lshl_add_u64 v[232:233], s[20:21], 0, v[130:131]
	s_mov_b32 m0, s47
	s_nop 0
	global_load_lds_dwordx4 v[232:233], off
	s_waitcnt vmcnt(8)
	s_waitcnt lgkmcnt(0)
	s_barrier
	s_setprio 1
	s_waitcnt lgkmcnt(0)
	v_mfma_f32_16x16x32_bf16 v[124:127], v[146:149], v[198:201], v[124:127]
	v_mfma_f32_16x16x32_bf16 v[124:127], v[152:155], v[202:205], v[124:127]
	v_mfma_f32_16x16x32_bf16 v[108:111], v[146:149], v[206:209], v[108:111]
	v_mfma_f32_16x16x32_bf16 v[108:111], v[152:155], v[210:213], v[108:111]
	v_mfma_f32_16x16x32_bf16 v[92:95], v[146:149], v[214:217], v[92:95]
	v_mfma_f32_16x16x32_bf16 v[92:95], v[152:155], v[218:221], v[92:95]
	v_mfma_f32_16x16x32_bf16 v[76:79], v[146:149], v[222:225], v[76:79]
	v_mfma_f32_16x16x32_bf16 v[76:79], v[152:155], v[226:229], v[76:79]
	v_mfma_f32_16x16x32_bf16 v[68:71], v[172:175], v[222:225], v[68:71]
	v_mfma_f32_16x16x32_bf16 v[68:71], v[178:181], v[226:229], v[68:71]
	v_mfma_f32_16x16x32_bf16 v[84:87], v[172:175], v[214:217], v[84:87]
	v_mfma_f32_16x16x32_bf16 v[84:87], v[178:181], v[218:221], v[84:87]
	v_mfma_f32_16x16x32_bf16 v[100:103], v[172:175], v[206:209], v[100:103]
	v_mfma_f32_16x16x32_bf16 v[100:103], v[178:181], v[210:213], v[100:103]
	v_mfma_f32_16x16x32_bf16 v[116:119], v[172:175], v[198:201], v[116:119]
	v_mfma_f32_16x16x32_bf16 v[116:119], v[178:181], v[202:205], v[116:119]
	s_setprio 0
	s_setprio 1
	v_mfma_f32_16x16x32_bf16 v[120:123], v[182:185], v[198:201], v[120:123]
	v_mfma_f32_16x16x32_bf16 v[120:123], v[186:189], v[202:205], v[120:123]
	v_mfma_f32_16x16x32_bf16 v[104:107], v[182:185], v[206:209], v[104:107]
	v_mfma_f32_16x16x32_bf16 v[104:107], v[186:189], v[210:213], v[104:107]
	v_mfma_f32_16x16x32_bf16 v[88:91], v[182:185], v[214:217], v[88:91]
	v_mfma_f32_16x16x32_bf16 v[88:91], v[186:189], v[218:221], v[88:91]
	v_mfma_f32_16x16x32_bf16 v[72:75], v[182:185], v[222:225], v[72:75]
	v_mfma_f32_16x16x32_bf16 v[72:75], v[186:189], v[226:229], v[72:75]
	v_mfma_f32_16x16x32_bf16 v[64:67], v[190:193], v[222:225], v[64:67]
	v_mfma_f32_16x16x32_bf16 v[64:67], v[194:197], v[226:229], v[64:67]
	v_mfma_f32_16x16x32_bf16 v[80:83], v[190:193], v[214:217], v[80:83]
	v_mfma_f32_16x16x32_bf16 v[80:83], v[194:197], v[218:221], v[80:83]
	v_mfma_f32_16x16x32_bf16 v[96:99], v[190:193], v[206:209], v[96:99]
	v_mfma_f32_16x16x32_bf16 v[96:99], v[194:197], v[210:213], v[96:99]
	v_mfma_f32_16x16x32_bf16 v[112:115], v[190:193], v[198:201], v[112:115]
	v_mfma_f32_16x16x32_bf16 v[112:115], v[194:197], v[202:205], v[112:115]
	s_setprio 0
	s_barrier
	s_add_i32 s20, s33, s42
	v_lshl_add_u64 v[158:159], v[158:159], 0, s[8:9]
	s_mov_b32 m0, s20
	ds_read_b128 v[198:201], v171 offset:49152
	ds_read_b128 v[202:205], v171 offset:50176
	ds_read_b128 v[206:209], v171 offset:51200
	ds_read_b128 v[210:213], v171 offset:52224
	ds_read_b128 v[214:217], v171 offset:53248
	ds_read_b128 v[218:221], v171 offset:54272
	ds_read_b128 v[222:225], v171 offset:55296
	ds_read_b128 v[226:229], v171 offset:56320
	global_load_lds_dwordx4 v[158:159], off
	s_add_i32 m0, s20, 0x2000
	s_add_u32 s20, s38, 0x40080
	v_lshl_add_u64 v[158:159], v[164:165], 0, s[8:9]
	s_addc_u32 s21, s39, 0
	s_add_i32 s33, s62, s42
	global_load_lds_dwordx4 v[158:159], off
	v_lshl_add_u64 v[158:159], s[20:21], 0, v[132:133]
	s_mov_b32 m0, s33
	s_nop 0
	global_load_lds_dwordx4 v[158:159], off
	v_lshl_add_u64 v[158:159], s[20:21], 0, v[128:129]
	s_add_i32 m0, s33, 0x2000
	s_nop 0
	global_load_lds_dwordx4 v[158:159], off
	v_lshl_add_u64 v[158:159], v[168:169], 0, s[8:9]
	s_mov_b32 m0, s49
	s_nop 0
	global_load_lds_dwordx4 v[158:159], off
	v_lshl_add_u64 v[158:159], v[230:231], 0, s[8:9]
	s_mov_b32 m0, s50
	s_nop 0
	global_load_lds_dwordx4 v[158:159], off
	s_waitcnt vmcnt(8)
	s_waitcnt lgkmcnt(0)
	s_barrier
	s_setprio 1
	s_waitcnt lgkmcnt(0)
	v_mfma_f32_16x16x32_bf16 v[60:63], v[146:149], v[198:201], v[60:63]
	v_mfma_f32_16x16x32_bf16 v[60:63], v[152:155], v[202:205], v[60:63]
	v_mfma_f32_16x16x32_bf16 v[44:47], v[146:149], v[206:209], v[44:47]
	v_mfma_f32_16x16x32_bf16 v[44:47], v[152:155], v[210:213], v[44:47]
	v_mfma_f32_16x16x32_bf16 v[28:31], v[146:149], v[214:217], v[28:31]
	v_mfma_f32_16x16x32_bf16 v[28:31], v[152:155], v[218:221], v[28:31]
	v_mfma_f32_16x16x32_bf16 v[12:15], v[146:149], v[222:225], v[12:15]
	v_mfma_f32_16x16x32_bf16 v[12:15], v[152:155], v[226:229], v[12:15]
	v_mfma_f32_16x16x32_bf16 v[4:7], v[172:175], v[222:225], v[4:7]
	v_mfma_f32_16x16x32_bf16 v[4:7], v[178:181], v[226:229], v[4:7]
	v_mfma_f32_16x16x32_bf16 v[20:23], v[172:175], v[214:217], v[20:23]
	v_mfma_f32_16x16x32_bf16 v[20:23], v[178:181], v[218:221], v[20:23]
	v_mfma_f32_16x16x32_bf16 v[36:39], v[172:175], v[206:209], v[36:39]
	v_mfma_f32_16x16x32_bf16 v[36:39], v[178:181], v[210:213], v[36:39]
	v_mfma_f32_16x16x32_bf16 v[52:55], v[172:175], v[198:201], v[52:55]
	v_mfma_f32_16x16x32_bf16 v[52:55], v[178:181], v[202:205], v[52:55]
	s_setprio 0
	s_setprio 1
	v_mfma_f32_16x16x32_bf16 v[56:59], v[182:185], v[198:201], v[56:59]
	v_mfma_f32_16x16x32_bf16 v[56:59], v[186:189], v[202:205], v[56:59]
	v_mfma_f32_16x16x32_bf16 v[40:43], v[182:185], v[206:209], v[40:43]
	v_mfma_f32_16x16x32_bf16 v[40:43], v[186:189], v[210:213], v[40:43]
	v_mfma_f32_16x16x32_bf16 v[24:27], v[182:185], v[214:217], v[24:27]
	v_mfma_f32_16x16x32_bf16 v[24:27], v[186:189], v[218:221], v[24:27]
	v_mfma_f32_16x16x32_bf16 v[8:11], v[182:185], v[222:225], v[8:11]
	v_mfma_f32_16x16x32_bf16 v[8:11], v[186:189], v[226:229], v[8:11]
	v_mfma_f32_16x16x32_bf16 v[0:3], v[190:193], v[222:225], v[0:3]
	v_mfma_f32_16x16x32_bf16 v[0:3], v[194:197], v[226:229], v[0:3]
	v_mfma_f32_16x16x32_bf16 v[16:19], v[190:193], v[214:217], v[16:19]
	v_mfma_f32_16x16x32_bf16 v[16:19], v[194:197], v[218:221], v[16:19]
	v_mfma_f32_16x16x32_bf16 v[32:35], v[190:193], v[206:209], v[32:35]
	v_mfma_f32_16x16x32_bf16 v[32:35], v[194:197], v[210:213], v[32:35]
	v_mfma_f32_16x16x32_bf16 v[48:51], v[190:193], v[198:201], v[48:51]
	v_mfma_f32_16x16x32_bf16 v[48:51], v[194:197], v[202:205], v[48:51]
	s_setprio 0
	s_barrier
	s_add_i32 s61, s61, 2
	s_add_u32 s36, s36, 0x100
	s_addc_u32 s37, s37, 0
	s_add_u32 s59, s59, 0x100
	s_addc_u32 s60, s60, 0
	s_cmp_gt_u32 s61, 13
	s_cbranch_scc0 .LBB0_721
	s_and_b64 vcc, exec, s[10:11]
	s_cbranch_vccz .LBB0_724
	s_barrier

.LBB0_801:
	ds_read_b128 v[128:131], v197
	ds_read_b128 v[132:135], v197 offset:1024
	ds_read_b128 v[136:139], v197 offset:2048
	ds_read_b128 v[140:143], v197 offset:3072
	ds_read_b128 v[144:147], v198
	ds_read_b128 v[148:151], v198 offset:1024
	ds_read_b128 v[152:155], v198 offset:2048
	ds_read_b128 v[156:159], v198 offset:3072
	s_add_u32 s16, s14, 0x100
	s_addc_u32 s17, s15, 0
	s_cmp_eq_u32 s47, 40
	s_cselect_b32 s21, s5, s17
	s_cselect_b32 s20, s4, s16
	s_cselect_b32 s19, s13, s46
	s_cselect_b32 s18, s12, s45
	v_lshl_add_u64 v[192:193], s[14:15], 0, v[172:173]
	s_add_i32 m0, s23, 0xc000
	ds_read_b128 v[160:163], v199
	ds_read_b128 v[180:183], v199 offset:1024
	ds_read_b128 v[184:187], v199 offset:2048
	ds_read_b128 v[188:191], v199 offset:3072
	ds_read_b128 v[200:203], v199 offset:4096
	ds_read_b128 v[204:207], v199 offset:5120
	ds_read_b128 v[208:211], v199 offset:6144
	ds_read_b128 v[212:215], v199 offset:7168
	global_load_lds_dwordx4 v[192:193], off
	v_lshl_add_u64 v[192:193], s[14:15], 0, v[174:175]
	s_add_i32 m0, s23, 0xe000
	s_nop 0
	global_load_lds_dwordx4 v[192:193], off
	s_waitcnt vmcnt(8)
	s_waitcnt lgkmcnt(0)
	s_barrier
	s_setprio 1
	s_waitcnt lgkmcnt(0)
	v_mfma_f32_16x16x32_bf16 v[124:127], v[128:131], v[160:163], v[124:127]
	v_mfma_f32_16x16x32_bf16 v[124:127], v[132:135], v[180:183], v[124:127]
	v_mfma_f32_16x16x32_bf16 v[112:115], v[128:131], v[184:187], v[112:115]
	v_mfma_f32_16x16x32_bf16 v[112:115], v[132:135], v[188:191], v[112:115]
	v_mfma_f32_16x16x32_bf16 v[96:99], v[128:131], v[200:203], v[96:99]
	v_mfma_f32_16x16x32_bf16 v[96:99], v[132:135], v[204:207], v[96:99]
	v_mfma_f32_16x16x32_bf16 v[80:83], v[128:131], v[208:211], v[80:83]
	v_mfma_f32_16x16x32_bf16 v[80:83], v[132:135], v[212:215], v[80:83]
	v_mfma_f32_16x16x32_bf16 v[72:75], v[136:139], v[208:211], v[72:75]
	v_mfma_f32_16x16x32_bf16 v[72:75], v[140:143], v[212:215], v[72:75]
	v_mfma_f32_16x16x32_bf16 v[88:91], v[136:139], v[200:203], v[88:91]
	v_mfma_f32_16x16x32_bf16 v[88:91], v[140:143], v[204:207], v[88:91]
	v_mfma_f32_16x16x32_bf16 v[104:107], v[136:139], v[184:187], v[104:107]
	v_mfma_f32_16x16x32_bf16 v[104:107], v[140:143], v[188:191], v[104:107]
	v_mfma_f32_16x16x32_bf16 v[120:123], v[136:139], v[160:163], v[120:123]
	v_mfma_f32_16x16x32_bf16 v[120:123], v[140:143], v[180:183], v[120:123]
	s_setprio 0
	s_setprio 1
	v_mfma_f32_16x16x32_bf16 v[116:119], v[144:147], v[160:163], v[116:119]
	v_mfma_f32_16x16x32_bf16 v[116:119], v[148:151], v[180:183], v[116:119]
	v_mfma_f32_16x16x32_bf16 v[100:103], v[144:147], v[184:187], v[100:103]
	v_mfma_f32_16x16x32_bf16 v[100:103], v[148:151], v[188:191], v[100:103]
	v_mfma_f32_16x16x32_bf16 v[84:87], v[144:147], v[200:203], v[84:87]
	v_mfma_f32_16x16x32_bf16 v[84:87], v[148:151], v[204:207], v[84:87]
	v_mfma_f32_16x16x32_bf16 v[68:71], v[144:147], v[208:211], v[68:71]
	v_mfma_f32_16x16x32_bf16 v[68:71], v[148:151], v[212:215], v[68:71]
	v_mfma_f32_16x16x32_bf16 v[64:67], v[152:155], v[208:211], v[64:67]
	v_mfma_f32_16x16x32_bf16 v[64:67], v[156:159], v[212:215], v[64:67]
	v_mfma_f32_16x16x32_bf16 v[76:79], v[152:155], v[200:203], v[76:79]
	v_mfma_f32_16x16x32_bf16 v[76:79], v[156:159], v[204:207], v[76:79]
	v_mfma_f32_16x16x32_bf16 v[92:95], v[152:155], v[184:187], v[92:95]
	v_mfma_f32_16x16x32_bf16 v[92:95], v[156:159], v[188:191], v[92:95]
	v_mfma_f32_16x16x32_bf16 v[108:111], v[152:155], v[160:163], v[108:111]
	v_mfma_f32_16x16x32_bf16 v[108:111], v[156:159], v[180:183], v[108:111]
	s_setprio 0
	s_barrier
	s_add_i32 s14, s39, s22
	v_lshl_add_u64 v[192:193], s[18:19], 0, v[166:167]
	s_mov_b32 m0, s14
	ds_read_b128 v[160:163], v199 offset:16384
	ds_read_b128 v[180:183], v199 offset:17408
	ds_read_b128 v[184:187], v199 offset:18432
	ds_read_b128 v[188:191], v199 offset:19456
	ds_read_b128 v[200:203], v199 offset:20480
	ds_read_b128 v[204:207], v199 offset:21504
	ds_read_b128 v[208:211], v199 offset:22528
	ds_read_b128 v[212:215], v199 offset:23552
	global_load_lds_dwordx4 v[192:193], off
	s_add_i32 m0, s14, 0x2000
	s_add_u32 s14, s18, 0xb0000
	v_lshl_add_u64 v[216:217], s[18:19], 0, v[170:171]
	s_addc_u32 s15, s19, 0
	s_add_i32 s48, s40, s22
	global_load_lds_dwordx4 v[216:217], off
	v_lshl_add_u64 v[218:219], s[14:15], 0, v[166:167]
	s_mov_b32 m0, s48
	v_lshl_add_u64 v[220:221], s[20:21], 0, v[168:169]
	global_load_lds_dwordx4 v[218:219], off
	v_lshl_add_u64 v[218:219], s[14:15], 0, v[170:171]
	s_add_i32 m0, s48, 0x2000
	s_nop 0
	global_load_lds_dwordx4 v[218:219], off
	v_lshl_add_u64 v[218:219], s[20:21], 0, v[164:165]
	s_mov_b32 m0, s23
	s_nop 0
	global_load_lds_dwordx4 v[218:219], off
	s_mov_b32 m0, s30
	s_nop 0
	global_load_lds_dwordx4 v[220:221], off
	s_waitcnt vmcnt(8)
	s_waitcnt lgkmcnt(0)
	s_barrier
	s_setprio 1
	s_waitcnt lgkmcnt(0)
	v_mfma_f32_16x16x32_bf16 v[60:63], v[128:131], v[160:163], v[60:63]
	v_mfma_f32_16x16x32_bf16 v[60:63], v[132:135], v[180:183], v[60:63]
	v_mfma_f32_16x16x32_bf16 v[48:51], v[128:131], v[184:187], v[48:51]
	v_mfma_f32_16x16x32_bf16 v[48:51], v[132:135], v[188:191], v[48:51]
	v_mfma_f32_16x16x32_bf16 v[32:35], v[128:131], v[200:203], v[32:35]
	v_mfma_f32_16x16x32_bf16 v[32:35], v[132:135], v[204:207], v[32:35]
	v_mfma_f32_16x16x32_bf16 v[16:19], v[128:131], v[208:211], v[16:19]
	v_mfma_f32_16x16x32_bf16 v[16:19], v[132:135], v[212:215], v[16:19]
	v_mfma_f32_16x16x32_bf16 v[8:11], v[136:139], v[208:211], v[8:11]
	v_mfma_f32_16x16x32_bf16 v[8:11], v[140:143], v[212:215], v[8:11]
	v_mfma_f32_16x16x32_bf16 v[24:27], v[136:139], v[200:203], v[24:27]
	v_mfma_f32_16x16x32_bf16 v[24:27], v[140:143], v[204:207], v[24:27]
	v_mfma_f32_16x16x32_bf16 v[40:43], v[136:139], v[184:187], v[40:43]
	v_mfma_f32_16x16x32_bf16 v[40:43], v[140:143], v[188:191], v[40:43]
	v_mfma_f32_16x16x32_bf16 v[56:59], v[136:139], v[160:163], v[56:59]
	v_mfma_f32_16x16x32_bf16 v[56:59], v[140:143], v[180:183], v[56:59]
	s_setprio 0
	s_setprio 1
	v_mfma_f32_16x16x32_bf16 v[52:55], v[144:147], v[160:163], v[52:55]
	v_mfma_f32_16x16x32_bf16 v[52:55], v[148:151], v[180:183], v[52:55]
	v_mfma_f32_16x16x32_bf16 v[36:39], v[144:147], v[184:187], v[36:39]
	v_mfma_f32_16x16x32_bf16 v[36:39], v[148:151], v[188:191], v[36:39]
	v_mfma_f32_16x16x32_bf16 v[20:23], v[144:147], v[200:203], v[20:23]
	v_mfma_f32_16x16x32_bf16 v[20:23], v[148:151], v[204:207], v[20:23]
	v_mfma_f32_16x16x32_bf16 v[4:7], v[144:147], v[208:211], v[4:7]
	v_mfma_f32_16x16x32_bf16 v[4:7], v[148:151], v[212:215], v[4:7]
	v_mfma_f32_16x16x32_bf16 v[0:3], v[152:155], v[208:211], v[0:3]
	v_mfma_f32_16x16x32_bf16 v[0:3], v[156:159], v[212:215], v[0:3]
	v_mfma_f32_16x16x32_bf16 v[12:15], v[152:155], v[200:203], v[12:15]
	v_mfma_f32_16x16x32_bf16 v[12:15], v[156:159], v[204:207], v[12:15]
	v_mfma_f32_16x16x32_bf16 v[28:31], v[152:155], v[184:187], v[28:31]
	v_mfma_f32_16x16x32_bf16 v[28:31], v[156:159], v[188:191], v[28:31]
	v_mfma_f32_16x16x32_bf16 v[44:47], v[152:155], v[160:163], v[44:47]
	v_mfma_f32_16x16x32_bf16 v[44:47], v[156:159], v[180:183], v[44:47]
	s_setprio 0
	s_barrier
	s_add_i32 s48, 0, 0x18000
	s_add_i32 s49, 0, 0x1c000
	v_add_u32_e32 v140, s48, v195
	v_add_u32_e32 v156, s49, v195
	ds_read_b128 v[128:131], v140
	ds_read_b128 v[132:135], v140 offset:1024
	ds_read_b128 v[136:139], v140 offset:2048
	ds_read_b128 v[140:143], v140 offset:3072
	ds_read_b128 v[144:147], v156
	ds_read_b128 v[148:151], v156 offset:1024
	ds_read_b128 v[152:155], v156 offset:2048
	ds_read_b128 v[156:159], v156 offset:3072
	s_add_u32 s14, s20, 0xb0000
	s_addc_u32 s15, s21, 0
	s_mov_b32 m0, s31
	v_lshl_add_u64 v[222:223], s[14:15], 0, v[164:165]
	ds_read_b128 v[160:163], v199 offset:32768
	ds_read_b128 v[180:183], v199 offset:33792
	ds_read_b128 v[184:187], v199 offset:34816
	ds_read_b128 v[188:191], v199 offset:35840
	ds_read_b128 v[200:203], v199 offset:36864
	ds_read_b128 v[204:207], v199 offset:37888
	ds_read_b128 v[208:211], v199 offset:38912
	ds_read_b128 v[212:215], v199 offset:39936
	global_load_lds_dwordx4 v[222:223], off
	v_lshl_add_u64 v[222:223], s[14:15], 0, v[168:169]
	s_mov_b32 m0, s33
	s_nop 0
	global_load_lds_dwordx4 v[222:223], off
	s_waitcnt vmcnt(8)
	s_waitcnt lgkmcnt(0)
	s_barrier
	s_setprio 1
	s_waitcnt lgkmcnt(0)
	v_mfma_f32_16x16x32_bf16 v[124:127], v[128:131], v[160:163], v[124:127]
	v_mfma_f32_16x16x32_bf16 v[124:127], v[132:135], v[180:183], v[124:127]
	v_mfma_f32_16x16x32_bf16 v[112:115], v[128:131], v[184:187], v[112:115]
	v_mfma_f32_16x16x32_bf16 v[112:115], v[132:135], v[188:191], v[112:115]
	v_mfma_f32_16x16x32_bf16 v[96:99], v[128:131], v[200:203], v[96:99]
	v_mfma_f32_16x16x32_bf16 v[96:99], v[132:135], v[204:207], v[96:99]
	v_mfma_f32_16x16x32_bf16 v[80:83], v[128:131], v[208:211], v[80:83]
	v_mfma_f32_16x16x32_bf16 v[80:83], v[132:135], v[212:215], v[80:83]
	v_mfma_f32_16x16x32_bf16 v[72:75], v[136:139], v[208:211], v[72:75]
	v_mfma_f32_16x16x32_bf16 v[72:75], v[140:143], v[212:215], v[72:75]
	v_mfma_f32_16x16x32_bf16 v[88:91], v[136:139], v[200:203], v[88:91]
	v_mfma_f32_16x16x32_bf16 v[88:91], v[140:143], v[204:207], v[88:91]
	v_mfma_f32_16x16x32_bf16 v[104:107], v[136:139], v[184:187], v[104:107]
	v_mfma_f32_16x16x32_bf16 v[104:107], v[140:143], v[188:191], v[104:107]
	v_mfma_f32_16x16x32_bf16 v[120:123], v[136:139], v[160:163], v[120:123]
	v_mfma_f32_16x16x32_bf16 v[120:123], v[140:143], v[180:183], v[120:123]
	s_setprio 0
	s_setprio 1
	v_mfma_f32_16x16x32_bf16 v[116:119], v[144:147], v[160:163], v[116:119]
	v_mfma_f32_16x16x32_bf16 v[116:119], v[148:151], v[180:183], v[116:119]
	v_mfma_f32_16x16x32_bf16 v[100:103], v[144:147], v[184:187], v[100:103]
	v_mfma_f32_16x16x32_bf16 v[100:103], v[148:151], v[188:191], v[100:103]
	v_mfma_f32_16x16x32_bf16 v[84:87], v[144:147], v[200:203], v[84:87]
	v_mfma_f32_16x16x32_bf16 v[84:87], v[148:151], v[204:207], v[84:87]
	v_mfma_f32_16x16x32_bf16 v[68:71], v[144:147], v[208:211], v[68:71]
	v_mfma_f32_16x16x32_bf16 v[68:71], v[148:151], v[212:215], v[68:71]
	v_mfma_f32_16x16x32_bf16 v[64:67], v[152:155], v[208:211], v[64:67]
	v_mfma_f32_16x16x32_bf16 v[64:67], v[156:159], v[212:215], v[64:67]
	v_mfma_f32_16x16x32_bf16 v[76:79], v[152:155], v[200:203], v[76:79]
	v_mfma_f32_16x16x32_bf16 v[76:79], v[156:159], v[204:207], v[76:79]
	v_mfma_f32_16x16x32_bf16 v[92:95], v[152:155], v[184:187], v[92:95]
	v_mfma_f32_16x16x32_bf16 v[92:95], v[156:159], v[188:191], v[92:95]
	v_mfma_f32_16x16x32_bf16 v[108:111], v[152:155], v[160:163], v[108:111]
	v_mfma_f32_16x16x32_bf16 v[108:111], v[156:159], v[180:183], v[108:111]
	s_setprio 0
	s_barrier
	s_add_i32 s14, s48, s22
	v_lshl_add_u64 v[192:193], v[192:193], 0, s[8:9]
	s_mov_b32 m0, s14
	ds_read_b128 v[160:163], v199 offset:49152
	ds_read_b128 v[180:183], v199 offset:50176
	ds_read_b128 v[184:187], v199 offset:51200
	ds_read_b128 v[188:191], v199 offset:52224
	ds_read_b128 v[200:203], v199 offset:53248
	ds_read_b128 v[204:207], v199 offset:54272
	ds_read_b128 v[208:211], v199 offset:55296
	ds_read_b128 v[212:215], v199 offset:56320
	global_load_lds_dwordx4 v[192:193], off
	s_add_i32 m0, s14, 0x2000
	s_add_u32 s14, s18, 0xb0080
	v_lshl_add_u64 v[192:193], v[216:217], 0, s[8:9]
	s_addc_u32 s15, s19, 0
	s_add_i32 s18, s49, s22
	global_load_lds_dwordx4 v[192:193], off
	v_lshl_add_u64 v[192:193], s[14:15], 0, v[166:167]
	s_mov_b32 m0, s18
	s_nop 0
	global_load_lds_dwordx4 v[192:193], off
	v_lshl_add_u64 v[192:193], s[14:15], 0, v[170:171]
	s_add_i32 m0, s18, 0x2000
	s_nop 0
	global_load_lds_dwordx4 v[192:193], off
	v_lshl_add_u64 v[192:193], v[218:219], 0, s[8:9]
	s_mov_b32 m0, s36
	s_nop 0
	global_load_lds_dwordx4 v[192:193], off
	v_lshl_add_u64 v[192:193], v[220:221], 0, s[8:9]
	s_mov_b32 m0, s37
	s_nop 0
	global_load_lds_dwordx4 v[192:193], off
	s_waitcnt vmcnt(8)
	s_waitcnt lgkmcnt(0)
	s_barrier
	s_setprio 1
	s_waitcnt lgkmcnt(0)
	v_mfma_f32_16x16x32_bf16 v[60:63], v[128:131], v[160:163], v[60:63]
	v_mfma_f32_16x16x32_bf16 v[60:63], v[132:135], v[180:183], v[60:63]
	v_mfma_f32_16x16x32_bf16 v[48:51], v[128:131], v[184:187], v[48:51]
	v_mfma_f32_16x16x32_bf16 v[48:51], v[132:135], v[188:191], v[48:51]
	v_mfma_f32_16x16x32_bf16 v[32:35], v[128:131], v[200:203], v[32:35]
	v_mfma_f32_16x16x32_bf16 v[32:35], v[132:135], v[204:207], v[32:35]
	v_mfma_f32_16x16x32_bf16 v[16:19], v[128:131], v[208:211], v[16:19]
	v_mfma_f32_16x16x32_bf16 v[16:19], v[132:135], v[212:215], v[16:19]
	v_mfma_f32_16x16x32_bf16 v[8:11], v[136:139], v[208:211], v[8:11]
	v_mfma_f32_16x16x32_bf16 v[8:11], v[140:143], v[212:215], v[8:11]
	v_mfma_f32_16x16x32_bf16 v[24:27], v[136:139], v[200:203], v[24:27]
	v_mfma_f32_16x16x32_bf16 v[24:27], v[140:143], v[204:207], v[24:27]
	v_mfma_f32_16x16x32_bf16 v[40:43], v[136:139], v[184:187], v[40:43]
	v_mfma_f32_16x16x32_bf16 v[40:43], v[140:143], v[188:191], v[40:43]
	v_mfma_f32_16x16x32_bf16 v[56:59], v[136:139], v[160:163], v[56:59]
	v_mfma_f32_16x16x32_bf16 v[56:59], v[140:143], v[180:183], v[56:59]
	s_setprio 0
	s_setprio 1
	v_mfma_f32_16x16x32_bf16 v[52:55], v[144:147], v[160:163], v[52:55]
	v_mfma_f32_16x16x32_bf16 v[52:55], v[148:151], v[180:183], v[52:55]
	v_mfma_f32_16x16x32_bf16 v[36:39], v[144:147], v[184:187], v[36:39]
	v_mfma_f32_16x16x32_bf16 v[36:39], v[148:151], v[188:191], v[36:39]
	v_mfma_f32_16x16x32_bf16 v[20:23], v[144:147], v[200:203], v[20:23]
	v_mfma_f32_16x16x32_bf16 v[20:23], v[148:151], v[204:207], v[20:23]
	v_mfma_f32_16x16x32_bf16 v[4:7], v[144:147], v[208:211], v[4:7]
	v_mfma_f32_16x16x32_bf16 v[4:7], v[148:151], v[212:215], v[4:7]
	v_mfma_f32_16x16x32_bf16 v[0:3], v[152:155], v[208:211], v[0:3]
	v_mfma_f32_16x16x32_bf16 v[0:3], v[156:159], v[212:215], v[0:3]
	v_mfma_f32_16x16x32_bf16 v[12:15], v[152:155], v[200:203], v[12:15]
	v_mfma_f32_16x16x32_bf16 v[12:15], v[156:159], v[204:207], v[12:15]
	v_mfma_f32_16x16x32_bf16 v[28:31], v[152:155], v[184:187], v[28:31]
	v_mfma_f32_16x16x32_bf16 v[28:31], v[156:159], v[188:191], v[28:31]
	v_mfma_f32_16x16x32_bf16 v[44:47], v[152:155], v[160:163], v[44:47]
	v_mfma_f32_16x16x32_bf16 v[44:47], v[156:159], v[180:183], v[44:47]
	s_setprio 0
	s_barrier
	s_add_i32 s47, s47, 2
	s_add_u32 s45, s45, 0x100
	s_addc_u32 s46, s46, 0
	s_cmp_gt_u32 s47, 41
	s_mov_b64 s[14:15], s[16:17]
	s_cbranch_scc0 .LBB0_801
	s_and_b64 vcc, exec, s[10:11]
	s_cbranch_vccz .LBB0_804
	s_barrier
